# ConvGate epilogue: sigmoid chains regenerated with packed f32 mul/add (v_pk_mul/v_pk_add), same f32 math, 64 fewer VALU per unit
# baseline (speedup 1.0000x reference)
.Lws__106_1:
	s_waitcnt lgkmcnt(0)
	s_barrier
	s_setprio 1
	s_waitcnt lgkmcnt(0)
	v_mfma_f32_16x16x32_bf16 v[94:97], v[130:133], v[186:189], v[94:97]
	v_mfma_f32_16x16x32_bf16 v[30:33], v[150:153], v[186:189], v[30:33]
	v_mfma_f32_16x16x32_bf16 v[78:81], v[130:133], v[194:197], v[78:81]
	v_mfma_f32_16x16x32_bf16 v[18:21], v[150:153], v[194:197], v[18:21]
	v_mfma_f32_16x16x32_bf16 v[74:77], v[130:133], v[202:205], v[74:77]
	v_mfma_f32_16x16x32_bf16 v[10:13], v[150:153], v[202:205], v[10:13]
	v_mfma_f32_16x16x32_bf16 v[86:89], v[130:133], v[230:233], v[86:89]
	v_mfma_f32_16x16x32_bf16 v[22:25], v[150:153], v[230:233], v[22:25]
	v_mfma_f32_16x16x32_bf16 v[94:97], v[134:137], v[190:193], v[94:97]
	v_mfma_f32_16x16x32_bf16 v[30:33], v[154:157], v[190:193], v[30:33]
	v_mfma_f32_16x16x32_bf16 v[78:81], v[134:137], v[198:201], v[78:81]
	v_mfma_f32_16x16x32_bf16 v[18:21], v[154:157], v[198:201], v[18:21]
	v_mfma_f32_16x16x32_bf16 v[74:77], v[134:137], v[226:229], v[74:77]
	v_mfma_f32_16x16x32_bf16 v[10:13], v[154:157], v[226:229], v[10:13]
	v_mfma_f32_16x16x32_bf16 v[86:89], v[134:137], v[234:237], v[86:89]
	v_mfma_f32_16x16x32_bf16 v[22:25], v[154:157], v[234:237], v[22:25]
	s_setprio 0
	s_setprio 1
	v_mfma_f32_16x16x32_bf16 v[90:93], v[170:173], v[186:189], v[90:93]
	v_mfma_f32_16x16x32_bf16 v[26:29], v[178:181], v[186:189], v[26:29]
	v_mfma_f32_16x16x32_bf16 v[70:73], v[170:173], v[194:197], v[70:73]
	v_mfma_f32_16x16x32_bf16 v[6:9], v[178:181], v[194:197], v[6:9]
	v_mfma_f32_16x16x32_bf16 v[66:69], v[170:173], v[202:205], v[66:69]
	v_mfma_f32_16x16x32_bf16 v[2:5], v[178:181], v[202:205], v[2:5]
	v_mfma_f32_16x16x32_bf16 v[82:85], v[170:173], v[230:233], v[82:85]
	v_mfma_f32_16x16x32_bf16 v[14:17], v[178:181], v[230:233], v[14:17]
	v_mfma_f32_16x16x32_bf16 v[90:93], v[174:177], v[190:193], v[90:93]
	v_mfma_f32_16x16x32_bf16 v[26:29], v[182:185], v[190:193], v[26:29]
	v_mfma_f32_16x16x32_bf16 v[70:73], v[174:177], v[198:201], v[70:73]
	v_mfma_f32_16x16x32_bf16 v[6:9], v[182:185], v[198:201], v[6:9]
	v_mfma_f32_16x16x32_bf16 v[66:69], v[174:177], v[226:229], v[66:69]
	v_mfma_f32_16x16x32_bf16 v[2:5], v[182:185], v[226:229], v[2:5]
	v_mfma_f32_16x16x32_bf16 v[82:85], v[174:177], v[234:237], v[82:85]
	v_mfma_f32_16x16x32_bf16 v[14:17], v[182:185], v[234:237], v[14:17]
	s_setprio 0
	s_barrier
	s_add_i32 s46, 0, 0x18000
	v_add_u32_e32 v0, s46, v223
	s_add_i32 s47, 0, 0x1c000
	ds_read_b128 v[130:133], v0
	ds_read_b128 v[134:137], v0 offset:1024
	ds_read_b128 v[150:153], v0 offset:2048
	ds_read_b128 v[154:157], v0 offset:3072
	v_add_u32_e32 v0, s47, v223
	ds_read_b128 v[170:173], v0
	ds_read_b128 v[174:177], v0 offset:1024
	ds_read_b128 v[178:181], v0 offset:2048
	ds_read_b128 v[182:185], v0 offset:3072
	s_add_u32 s4, s4, 0x40000
	s_addc_u32 s5, s5, 0
	s_mov_b32 m0, s15
	v_lshl_add_u64 v[242:243], s[4:5], 0, v[138:139]
	ds_read_b128 v[186:189], v225 offset:32768
	ds_read_b128 v[190:193], v225 offset:33792
	ds_read_b128 v[194:197], v225 offset:34816
	ds_read_b128 v[198:201], v225 offset:35840
	ds_read_b128 v[202:205], v225 offset:36864
	ds_read_b128 v[226:229], v225 offset:37888
	ds_read_b128 v[230:233], v225 offset:38912
	ds_read_b128 v[234:237], v225 offset:39936
	global_load_lds_dwordx4 v[242:243], off
	v_lshl_add_u64 v[242:243], s[4:5], 0, v[142:143]
	s_mov_b32 m0, s16
	s_nop 0
	global_load_lds_dwordx4 v[242:243], off
	s_waitcnt vmcnt(8)
	s_waitcnt lgkmcnt(0)
	s_barrier
	s_setprio 1
	s_waitcnt lgkmcnt(0)
	v_mfma_f32_16x16x32_bf16 v[126:129], v[130:133], v[186:189], v[126:129]
	v_mfma_f32_16x16x32_bf16 v[62:65], v[150:153], v[186:189], v[62:65]
	v_mfma_f32_16x16x32_bf16 v[110:113], v[130:133], v[194:197], v[110:113]
	v_mfma_f32_16x16x32_bf16 v[46:49], v[150:153], v[194:197], v[46:49]
	v_mfma_f32_16x16x32_bf16 v[106:109], v[130:133], v[202:205], v[106:109]
	v_mfma_f32_16x16x32_bf16 v[42:45], v[150:153], v[202:205], v[42:45]
	v_mfma_f32_16x16x32_bf16 v[118:121], v[130:133], v[230:233], v[118:121]
	v_mfma_f32_16x16x32_bf16 v[54:57], v[150:153], v[230:233], v[54:57]
	v_mfma_f32_16x16x32_bf16 v[126:129], v[134:137], v[190:193], v[126:129]
	v_mfma_f32_16x16x32_bf16 v[62:65], v[154:157], v[190:193], v[62:65]
	v_mfma_f32_16x16x32_bf16 v[110:113], v[134:137], v[198:201], v[110:113]
	v_mfma_f32_16x16x32_bf16 v[46:49], v[154:157], v[198:201], v[46:49]
	v_mfma_f32_16x16x32_bf16 v[106:109], v[134:137], v[226:229], v[106:109]
	v_mfma_f32_16x16x32_bf16 v[42:45], v[154:157], v[226:229], v[42:45]
	v_mfma_f32_16x16x32_bf16 v[118:121], v[134:137], v[234:237], v[118:121]
	v_mfma_f32_16x16x32_bf16 v[54:57], v[154:157], v[234:237], v[54:57]
	s_setprio 0
	s_setprio 1
	v_mfma_f32_16x16x32_bf16 v[122:125], v[170:173], v[186:189], v[122:125]
	v_mfma_f32_16x16x32_bf16 v[58:61], v[178:181], v[186:189], v[58:61]
	v_mfma_f32_16x16x32_bf16 v[102:105], v[170:173], v[194:197], v[102:105]
	v_mfma_f32_16x16x32_bf16 v[38:41], v[178:181], v[194:197], v[38:41]
	v_mfma_f32_16x16x32_bf16 v[98:101], v[170:173], v[202:205], v[98:101]
	v_mfma_f32_16x16x32_bf16 v[34:37], v[178:181], v[202:205], v[34:37]
	v_mfma_f32_16x16x32_bf16 v[114:117], v[170:173], v[230:233], v[114:117]
	v_mfma_f32_16x16x32_bf16 v[50:53], v[178:181], v[230:233], v[50:53]
	v_mfma_f32_16x16x32_bf16 v[122:125], v[174:177], v[190:193], v[122:125]
	v_mfma_f32_16x16x32_bf16 v[58:61], v[182:185], v[190:193], v[58:61]
	v_mfma_f32_16x16x32_bf16 v[102:105], v[174:177], v[198:201], v[102:105]
	v_mfma_f32_16x16x32_bf16 v[38:41], v[182:185], v[198:201], v[38:41]
	v_mfma_f32_16x16x32_bf16 v[98:101], v[174:177], v[226:229], v[98:101]
	v_mfma_f32_16x16x32_bf16 v[34:37], v[182:185], v[226:229], v[34:37]
	v_mfma_f32_16x16x32_bf16 v[114:117], v[174:177], v[234:237], v[114:117]
	v_mfma_f32_16x16x32_bf16 v[50:53], v[182:185], v[234:237], v[50:53]
	s_setprio 0
	s_barrier
	s_add_i32 s4, s46, s12
	v_lshl_add_u64 v[158:159], v[158:159], 0, s[80:81]
	s_mov_b32 m0, s4
	ds_read_b128 v[186:189], v225 offset:49152
	ds_read_b128 v[190:193], v225 offset:50176
	ds_read_b128 v[194:197], v225 offset:51200
	ds_read_b128 v[198:201], v225 offset:52224
	ds_read_b128 v[202:205], v225 offset:53248
	ds_read_b128 v[226:229], v225 offset:54272
	ds_read_b128 v[230:233], v225 offset:55296
	ds_read_b128 v[234:237], v225 offset:56320
	global_load_lds_dwordx4 v[158:159], off
	s_add_i32 m0, s4, 0x2000
	s_add_u32 s0, s0, 0x40080
	v_lshl_add_u64 v[158:159], v[206:207], 0, s[80:81]
	s_addc_u32 s1, s1, 0
	s_add_i32 s4, s47, s12
	global_load_lds_dwordx4 v[158:159], off
	v_lshl_add_u64 v[158:159], s[0:1], 0, v[140:141]
	s_mov_b32 m0, s4
	s_nop 0
	global_load_lds_dwordx4 v[158:159], off
	v_lshl_add_u64 v[158:159], s[0:1], 0, v[144:145]
	s_add_i32 m0, s4, 0x2000
	s_nop 0
	global_load_lds_dwordx4 v[158:159], off
	v_lshl_add_u64 v[158:159], v[238:239], 0, s[80:81]
	s_mov_b32 m0, s22
	s_nop 0
	global_load_lds_dwordx4 v[158:159], off
	v_lshl_add_u64 v[158:159], v[240:241], 0, s[80:81]
	s_mov_b32 m0, s23
	s_nop 0
	global_load_lds_dwordx4 v[158:159], off
	s_waitcnt vmcnt(8)
	s_waitcnt lgkmcnt(0)
	s_barrier
	s_setprio 1
	s_waitcnt lgkmcnt(0)
	v_mfma_f32_16x16x32_bf16 v[94:97], v[130:133], v[186:189], v[94:97]
	v_mfma_f32_16x16x32_bf16 v[30:33], v[150:153], v[186:189], v[30:33]
	v_mfma_f32_16x16x32_bf16 v[78:81], v[130:133], v[194:197], v[78:81]
	v_mfma_f32_16x16x32_bf16 v[18:21], v[150:153], v[194:197], v[18:21]
	v_mfma_f32_16x16x32_bf16 v[74:77], v[130:133], v[202:205], v[74:77]
	v_mfma_f32_16x16x32_bf16 v[10:13], v[150:153], v[202:205], v[10:13]
	v_mfma_f32_16x16x32_bf16 v[86:89], v[130:133], v[230:233], v[86:89]
	v_mfma_f32_16x16x32_bf16 v[22:25], v[150:153], v[230:233], v[22:25]
	v_mfma_f32_16x16x32_bf16 v[94:97], v[134:137], v[190:193], v[94:97]
	v_mfma_f32_16x16x32_bf16 v[30:33], v[154:157], v[190:193], v[30:33]
	v_mfma_f32_16x16x32_bf16 v[78:81], v[134:137], v[198:201], v[78:81]
	v_mfma_f32_16x16x32_bf16 v[18:21], v[154:157], v[198:201], v[18:21]
	v_mfma_f32_16x16x32_bf16 v[74:77], v[134:137], v[226:229], v[74:77]
	v_mfma_f32_16x16x32_bf16 v[10:13], v[154:157], v[226:229], v[10:13]
	v_mfma_f32_16x16x32_bf16 v[86:89], v[134:137], v[234:237], v[86:89]
	v_mfma_f32_16x16x32_bf16 v[22:25], v[154:157], v[234:237], v[22:25]
	s_setprio 0
	s_setprio 1
	v_mfma_f32_16x16x32_bf16 v[90:93], v[170:173], v[186:189], v[90:93]
	v_mfma_f32_16x16x32_bf16 v[26:29], v[178:181], v[186:189], v[26:29]
	v_mfma_f32_16x16x32_bf16 v[70:73], v[170:173], v[194:197], v[70:73]
	v_mfma_f32_16x16x32_bf16 v[6:9], v[178:181], v[194:197], v[6:9]
	v_mfma_f32_16x16x32_bf16 v[66:69], v[170:173], v[202:205], v[66:69]
	v_mfma_f32_16x16x32_bf16 v[2:5], v[178:181], v[202:205], v[2:5]
	v_mfma_f32_16x16x32_bf16 v[82:85], v[170:173], v[230:233], v[82:85]
	v_mfma_f32_16x16x32_bf16 v[14:17], v[178:181], v[230:233], v[14:17]
	v_mfma_f32_16x16x32_bf16 v[90:93], v[174:177], v[190:193], v[90:93]
	v_mfma_f32_16x16x32_bf16 v[26:29], v[182:185], v[190:193], v[26:29]
	v_mfma_f32_16x16x32_bf16 v[70:73], v[174:177], v[198:201], v[70:73]
	v_mfma_f32_16x16x32_bf16 v[6:9], v[182:185], v[198:201], v[6:9]
	v_mfma_f32_16x16x32_bf16 v[66:69], v[174:177], v[226:229], v[66:69]
	v_mfma_f32_16x16x32_bf16 v[2:5], v[182:185], v[226:229], v[2:5]
	v_mfma_f32_16x16x32_bf16 v[82:85], v[174:177], v[234:237], v[82:85]
	v_mfma_f32_16x16x32_bf16 v[14:17], v[182:185], v[234:237], v[14:17]
	s_setprio 0
	s_barrier
	s_add_i32 s35, s35, 2
	s_add_u32 s42, s42, 0x100
	s_addc_u32 s43, s43, 0
	s_add_u32 s29, s29, 0x100
	s_addc_u32 s34, s34, 0
	s_cmp_gt_u32 s35, 13
	s_cbranch_scc0 .LBB0_106
	s_mov_b32 s98, 0xbfb8aa3b
	s_and_b64 vcc, exec, s[56:57]
	s_cbranch_vccz .LBB0_109
	s_barrier

.LBB0_113:
	s_or_b64 exec, exec, s[0:1]
	v_ffbh_u32_e32 v0, v135
	v_min_u32_e32 v0, 32, v0
	v_lshlrev_b64 v[114:115], v0, v[134:135]
	v_min_u32_e32 v114, 1, v114
	v_or_b32_e32 v114, v115, v114
	v_cvt_f32_u32_e32 v114, v114
	v_sub_u32_e32 v0, 32, v0
	s_lshl_b32 s5, s78, 7
	v_add_u32_e32 v180, s5, v130
	v_ldexp_f32 v0, v114, v0
	v_mul_f32_e32 v0, 0x33800000, v0
	v_fmamk_f32 v0, v0, 0x3a800000, v210
	s_nop 0
	v_rsq_f32_e32 v0, v0
	s_nop 0
	s_nop 0
	v_mov_b32_e32 v178, v0
	v_ffbh_u32_e32 v0, v133
	v_min_u32_e32 v0, 32, v0
	v_pk_mul_f32 v[186:187], v[110:111], v[178:179] op_sel_hi:[1,0]
	v_lshlrev_b64 v[110:111], v0, v[132:133]
	v_min_u32_e32 v110, 1, v110
	v_or_b32_e32 v110, v111, v110
	v_cvt_f32_u32_e32 v110, v110
	v_sub_u32_e32 v0, 32, v0
	v_pk_mul_f32 v[184:185], v[112:113], v[178:179] op_sel_hi:[1,0]
	v_ldexp_f32 v0, v110, v0
	v_mul_f32_e32 v0, 0x33800000, v0
	v_fmamk_f32 v0, v0, 0x3a800000, v210
	s_nop 0
	v_rsq_f32_e32 v0, v0
	s_nop 0
	s_nop 0
	v_mov_b32_e32 v182, v0
	v_pk_mul_f32 v[188:189], v[108:109], v[182:183] op_sel_hi:[1,0]
	v_pk_mul_f32 v[198:199], v[106:107], v[182:183] op_sel_hi:[1,0]
	v_ashrrev_i32_e32 v181, 31, v180
	v_lshlrev_b64 v[118:119], 2, v[180:181]
	v_lshl_add_u64 v[106:107], s[44:45], 0, v[118:119]
	v_lshl_add_u64 v[108:109], s[60:61], 0, v[118:119]
	global_load_dwordx4 v[122:125], v[106:107], off
	global_load_dwordx4 v[126:129], v[108:109], off
	v_lshl_add_u64 v[106:107], s[2:3], 0, v[118:119]
	global_load_dwordx4 v[130:133], v[106:107], off
	v_lshl_add_u64 v[106:107], s[48:49], 0, v[118:119]
	global_load_dwordx4 v[134:137], v[106:107], off
	s_nop 1
	v_cmp_lt_u32_e32 vcc, 1, v183
	v_mov_b32_dpp v206, v170 row_ror:1 row_mask:0xf bank_mask:0xf
	v_mov_b32_dpp v204, v170 row_ror:2 row_mask:0xf bank_mask:0xf
	v_mov_b32_dpp v207, v171 row_ror:1 row_mask:0xf bank_mask:0xf
	v_mov_b32_dpp v205, v171 row_ror:2 row_mask:0xf bank_mask:0xf
	v_mov_b32_dpp v202, v172 row_ror:1 row_mask:0xf bank_mask:0xf
	v_mov_b32_dpp v200, v172 row_ror:2 row_mask:0xf bank_mask:0xf
	v_mov_b32_dpp v203, v173 row_ror:1 row_mask:0xf bank_mask:0xf
	v_mov_b32_dpp v201, v173 row_ror:2 row_mask:0xf bank_mask:0xf
	v_mov_b32_dpp v241, v186 row_ror:1 row_mask:0xf bank_mask:0xf
	v_mov_b32_dpp v240, v186 row_ror:2 row_mask:0xf bank_mask:0xf
	v_mov_b32_dpp v245, v187 row_ror:1 row_mask:0xf bank_mask:0xf
	v_mov_b32_dpp v244, v187 row_ror:2 row_mask:0xf bank_mask:0xf
	v_mov_b32_dpp v229, v184 row_ror:1 row_mask:0xf bank_mask:0xf
	v_mov_b32_dpp v228, v184 row_ror:2 row_mask:0xf bank_mask:0xf
	v_mov_b32_dpp v235, v185 row_ror:1 row_mask:0xf bank_mask:0xf
	v_mov_b32_dpp v233, v185 row_ror:2 row_mask:0xf bank_mask:0xf
	v_mov_b32_dpp v234, v198 row_ror:1 row_mask:0xf bank_mask:0xf
	v_mov_b32_dpp v231, v198 row_ror:2 row_mask:0xf bank_mask:0xf
	v_mov_b32_dpp v239, v199 row_ror:1 row_mask:0xf bank_mask:0xf
	v_mov_b32_dpp v237, v199 row_ror:2 row_mask:0xf bank_mask:0xf
	v_mov_b32_dpp v151, v188 row_ror:1 row_mask:0xf bank_mask:0xf
	v_mov_b32_dpp v0, v188 row_ror:2 row_mask:0xf bank_mask:0xf
	v_mov_b32_dpp v227, v189 row_ror:1 row_mask:0xf bank_mask:0xf
	v_mov_b32_dpp v213, v189 row_ror:2 row_mask:0xf bank_mask:0xf
	v_mov_b32_dpp v243, v176 row_ror:1 row_mask:0xf bank_mask:0xf
	v_mov_b32_dpp v242, v176 row_ror:2 row_mask:0xf bank_mask:0xf
	v_mov_b32_dpp v247, v177 row_ror:1 row_mask:0xf bank_mask:0xf
	v_mov_b32_dpp v246, v177 row_ror:2 row_mask:0xf bank_mask:0xf
	v_mov_b32_dpp v232, v174 row_ror:1 row_mask:0xf bank_mask:0xf
	v_mov_b32_dpp v230, v174 row_ror:2 row_mask:0xf bank_mask:0xf
	v_mov_b32_dpp v238, v175 row_ror:1 row_mask:0xf bank_mask:0xf
	v_mov_b32_dpp v236, v175 row_ror:2 row_mask:0xf bank_mask:0xf
	v_lshl_add_u64 v[106:107], s[96:97], 0, v[118:119]
	v_lshl_add_u64 v[108:109], s[62:63], 0, v[118:119]
	global_load_dwordx4 v[114:117], v[106:107], off
	global_load_dwordx4 v[110:113], v[108:109], off
	v_lshl_add_u64 v[106:107], s[64:65], 0, v[118:119]
	v_lshl_add_u64 v[118:119], s[66:67], 0, v[118:119]
	global_load_dwordx4 v[106:109], v[106:107], off
	s_nop 1
	global_load_dwordx4 v[118:121], v[118:119], off
	s_nop 1
	v_mov_b32_dpp v190, v158 row_ror:1 row_mask:0xf bank_mask:0xf
	v_mov_b32_dpp v194, v158 row_ror:2 row_mask:0xf bank_mask:0xf
	v_mov_b32_dpp v191, v159 row_ror:1 row_mask:0xf bank_mask:0xf
	v_mov_b32_dpp v195, v159 row_ror:2 row_mask:0xf bank_mask:0xf
	v_mov_b32_dpp v192, v156 row_ror:1 row_mask:0xf bank_mask:0xf
	v_mov_b32_dpp v196, v156 row_ror:2 row_mask:0xf bank_mask:0xf
	v_mov_b32_dpp v193, v157 row_ror:1 row_mask:0xf bank_mask:0xf
	v_mov_b32_dpp v197, v157 row_ror:2 row_mask:0xf bank_mask:0xf
	s_and_saveexec_b64 s[0:1], vcc
	s_mov_b32 s50, 0x20000
	s_mov_b32 s47, 0xbfb8aa3b
	s_cbranch_execz .Lcg_skip0
	s_waitcnt vmcnt(4)
	v_pk_fma_f32 v[248:249], v[124:125], v[200:201], v[136:137]
	s_nop 0
	v_pk_fma_f32 v[248:249], v[128:129], v[202:203], v[248:249]
	s_nop 0
	v_pk_fma_f32 v[172:173], v[172:173], v[132:133], v[248:249]
	v_pk_fma_f32 v[248:249], v[122:123], v[204:205], v[134:135]
	v_pk_fma_f32 v[248:249], v[126:127], v[206:207], v[248:249]
	v_pk_fma_f32 v[170:171], v[170:171], v[130:131], v[248:249]
	v_pk_mul_f32 v[248:249], v[170:171], s[98:99] op_sel_hi:[1,0]
	v_pk_mul_f32 v[250:251], v[172:173], s[98:99] op_sel_hi:[1,0]
	v_exp_f32_e32 v248, v248
	v_exp_f32_e32 v249, v249
	v_exp_f32_e32 v250, v250
	v_exp_f32_e32 v251, v251
	v_pk_add_f32 v[248:249], v[248:249], 1.0 op_sel_hi:[1,0]
	v_pk_add_f32 v[250:251], v[250:251], 1.0 op_sel_hi:[1,0]
	v_rcp_f32_e32 v248, v248
	v_rcp_f32_e32 v249, v249
	v_rcp_f32_e32 v250, v250
	v_rcp_f32_e32 v251, v251
	v_pk_mul_f32 v[170:171], v[170:171], v[248:249]
	v_pk_mul_f32 v[172:173], v[172:173], v[250:251]
	s_waitcnt vmcnt(0)
	v_pk_fma_f32 v[248:249], v[116:117], v[196:197], v[120:121]
	v_pk_fma_f32 v[250:251], v[114:115], v[194:195], v[118:119]
	v_pk_fma_f32 v[248:249], v[112:113], v[192:193], v[248:249]
	v_pk_fma_f32 v[250:251], v[110:111], v[190:191], v[250:251]
	v_pk_fma_f32 v[156:157], v[156:157], v[108:109], v[248:249]
	v_pk_fma_f32 v[158:159], v[158:159], v[106:107], v[250:251]
	v_pk_mul_f32 v[156:157], v[172:173], v[156:157]
	v_pk_mul_f32 v[158:159], v[170:171], v[158:159]
	s_nop 0
	v_cvt_pk_bf16_f32 v158, v158, v159
	v_cvt_pk_bf16_f32 v159, v156, v157
	v_mov_b64_e32 v[156:157], s[36:37]
	v_mad_i64_i32 v[156:157], s[28:29], v150, s46, v[156:157]
	v_lshl_add_u64 v[156:157], v[180:181], 1, v[156:157]
	global_store_dwordx2 v[156:157], v[158:159], off
.LBB0_115:
	s_or_b64 exec, exec, s[0:1]
	v_cmp_eq_u32_e64 s[42:43], 0, v183
	v_cndmask_b32_e32 v159, v205, v244, vcc
	v_cndmask_b32_e32 v158, v204, v240, vcc
	v_cndmask_b32_e64 v157, v245, v207, s[42:43]
	v_cndmask_b32_e64 v156, v241, v206, s[42:43]
	s_waitcnt vmcnt(4)
	v_pk_fma_f32 v[158:159], v[122:123], v[158:159], v[134:135]
	v_cndmask_b32_e32 v173, v201, v233, vcc
	v_cndmask_b32_e32 v172, v200, v228, vcc
	v_pk_fma_f32 v[156:157], v[126:127], v[156:157], v[158:159]
	v_cndmask_b32_e64 v171, v235, v203, s[42:43]
	v_cndmask_b32_e64 v170, v229, v202, s[42:43]
	v_pk_fma_f32 v[172:173], v[124:125], v[172:173], v[136:137]
	v_pk_fma_f32 v[156:157], v[186:187], v[130:131], v[156:157]
	v_pk_fma_f32 v[170:171], v[128:129], v[170:171], v[172:173]
	v_cndmask_b32_e32 v187, v244, v237, vcc
	v_cndmask_b32_e32 v186, v240, v231, vcc
	v_pk_fma_f32 v[170:171], v[184:185], v[132:133], v[170:171]
	v_cndmask_b32_e64 v185, v239, v245, s[42:43]
	v_cndmask_b32_e64 v184, v234, v241, s[42:43]
	v_pk_fma_f32 v[186:187], v[122:123], v[186:187], v[134:135]
	v_cndmask_b32_e32 v201, v233, v213, vcc
	v_pk_fma_f32 v[184:185], v[126:127], v[184:185], v[186:187]
	v_cndmask_b32_e32 v200, v228, v0, vcc
	v_pk_fma_f32 v[184:185], v[198:199], v[130:131], v[184:185]
	v_cndmask_b32_e64 v199, v227, v235, s[42:43]
	v_cndmask_b32_e64 v198, v151, v229, s[42:43]
	v_pk_fma_f32 v[200:201], v[124:125], v[200:201], v[136:137]
	v_cndmask_b32_e32 v203, v237, v246, vcc
	v_cndmask_b32_e32 v202, v231, v242, vcc
	v_pk_fma_f32 v[198:199], v[128:129], v[198:199], v[200:201]
	v_cndmask_b32_e64 v201, v247, v239, s[42:43]
	v_cndmask_b32_e64 v200, v243, v234, s[42:43]
	v_pk_fma_f32 v[122:123], v[122:123], v[202:203], v[134:135]
	v_cndmask_b32_e32 v135, v213, v236, vcc
	v_pk_fma_f32 v[122:123], v[126:127], v[200:201], v[122:123]
	v_cndmask_b32_e32 v134, v0, v230, vcc
	v_pk_fma_f32 v[122:123], v[176:177], v[130:131], v[122:123]
	v_cndmask_b32_e64 v131, v238, v227, s[42:43]
	v_cndmask_b32_e64 v130, v232, v151, s[42:43]
	v_pk_fma_f32 v[124:125], v[124:125], v[134:135], v[136:137]
	v_pk_fma_f32 v[124:125], v[128:129], v[130:131], v[124:125]
	v_mov_b32_e32 v179, v178
	v_pk_fma_f32 v[124:125], v[174:175], v[132:133], v[124:125]
	v_mov_b32_e32 v183, v182
	v_mov_b32_e32 v130, v178
	v_mov_b32_e32 v131, v178
	v_pk_mul_f32 v[104:105], v[104:105], v[130:131]
	v_pk_mul_f32 v[102:103], v[102:103], v[178:179]
	v_pk_mul_f32 v[98:99], v[98:99], v[182:183]
	s_nop 1
	v_mov_b32_e32 v130, v182
	v_mov_b32_e32 v131, v182
	s_nop 1
	v_mov_b32_dpp v177, v102 row_ror:2 row_mask:0xf bank_mask:0xf
	s_nop 1
	v_mov_b32_dpp v179, v103 row_ror:2 row_mask:0xf bank_mask:0xf
	s_nop 1
	v_mov_b32_dpp v183, v104 row_ror:2 row_mask:0xf bank_mask:0xf
	s_nop 1
	v_mov_b32_dpp v201, v105 row_ror:2 row_mask:0xf bank_mask:0xf
	v_pk_fma_f32 v[188:189], v[188:189], v[132:133], v[198:199]
	v_pk_mul_f32 v[100:101], v[100:101], v[130:131]
	v_mov_b32_dpp v176, v102 row_ror:1 row_mask:0xf bank_mask:0xf
	v_mov_b32_dpp v178, v103 row_ror:1 row_mask:0xf bank_mask:0xf
	v_mov_b32_dpp v182, v104 row_ror:1 row_mask:0xf bank_mask:0xf
	v_mov_b32_dpp v200, v105 row_ror:1 row_mask:0xf bank_mask:0xf
	v_cndmask_b32_e32 v130, v194, v177, vcc
	v_cndmask_b32_e32 v131, v195, v179, vcc
	v_cndmask_b32_e32 v132, v196, v183, vcc
	v_cndmask_b32_e32 v133, v197, v201, vcc
	v_cndmask_b32_e64 v134, v176, v190, s[42:43]
	v_cndmask_b32_e64 v135, v178, v191, s[42:43]
	v_cndmask_b32_e64 v136, v182, v192, s[42:43]
	v_cndmask_b32_e64 v137, v200, v193, s[42:43]
	s_waitcnt vmcnt(1)
	v_pk_fma_f32 v[132:133], v[116:117], v[132:133], v[120:121]
	v_pk_fma_f32 v[130:131], v[114:115], v[130:131], v[118:119]
	v_pk_fma_f32 v[132:133], v[112:113], v[136:137], v[132:133]
	v_pk_fma_f32 v[130:131], v[110:111], v[134:135], v[130:131]
	v_or_b32_e32 v0, 16, v150
	v_or_b32_e32 v174, 32, v150
	v_or_b32_e32 v175, 48, v150
	v_pk_mul_f32 v[158:159], v[156:157], s[98:99] op_sel_hi:[1,0]
	v_pk_mul_f32 v[172:173], v[170:171], s[98:99] op_sel_hi:[1,0]
	v_exp_f32_e32 v158, v158
	v_exp_f32_e32 v159, v159
	v_exp_f32_e32 v172, v172
	v_exp_f32_e32 v173, v173
	v_pk_add_f32 v[158:159], v[158:159], 1.0 op_sel_hi:[1,0]
	v_pk_add_f32 v[172:173], v[172:173], 1.0 op_sel_hi:[1,0]
	v_rcp_f32_e32 v158, v158
	v_rcp_f32_e32 v159, v159
	v_rcp_f32_e32 v172, v172
	v_rcp_f32_e32 v173, v173
	v_pk_mul_f32 v[150:151], v[156:157], v[158:159]
	v_pk_mul_f32 v[156:157], v[170:171], v[172:173]
	v_pk_fma_f32 v[104:105], v[104:105], v[108:109], v[132:133]
	v_pk_fma_f32 v[102:103], v[102:103], v[106:107], v[130:131]
	v_pk_mul_f32 v[104:105], v[156:157], v[104:105]
	v_pk_mul_f32 v[102:103], v[150:151], v[102:103]
	v_cvt_pk_bf16_f32 v102, v102, v103
	v_cvt_pk_bf16_f32 v103, v104, v105
	v_mov_b64_e32 v[104:105], s[36:37]
	v_mad_i64_i32 v[130:131], s[0:1], v0, s46, v[104:105]
	v_lshlrev_b64 v[132:133], 1, v[180:181]
	s_nop 1
	v_lshl_add_u64 v[130:131], v[130:131], 0, v[132:133]
	s_nop 1
	v_mov_b32_dpp v158, v98 row_ror:2 row_mask:0xf bank_mask:0xf
	s_nop 1
	v_mov_b32_dpp v170, v99 row_ror:2 row_mask:0xf bank_mask:0xf
	s_nop 1
	v_mov_b32_dpp v172, v100 row_ror:2 row_mask:0xf bank_mask:0xf
	s_nop 1
	v_mov_b32_dpp v180, v101 row_ror:2 row_mask:0xf bank_mask:0xf
	global_store_dwordx2 v[130:131], v[102:103], off
	v_mov_b32_dpp v0, v98 row_ror:1 row_mask:0xf bank_mask:0xf
	v_mov_b32_dpp v159, v99 row_ror:1 row_mask:0xf bank_mask:0xf
	v_mov_b32_dpp v171, v100 row_ror:1 row_mask:0xf bank_mask:0xf
	v_mov_b32_dpp v173, v101 row_ror:1 row_mask:0xf bank_mask:0xf
	v_cndmask_b32_e32 v102, v177, v158, vcc
	v_cndmask_b32_e32 v103, v179, v170, vcc
	v_cndmask_b32_e32 v130, v183, v172, vcc
	v_cndmask_b32_e32 v131, v201, v180, vcc
	v_cndmask_b32_e64 v134, v0, v176, s[42:43]
	v_cndmask_b32_e64 v135, v159, v178, s[42:43]
	v_cndmask_b32_e64 v136, v171, v182, s[42:43]
	v_cndmask_b32_e64 v137, v173, v200, s[42:43]
	v_pk_fma_f32 v[130:131], v[116:117], v[130:131], v[120:121]
	v_pk_fma_f32 v[102:103], v[114:115], v[102:103], v[118:119]
	v_pk_fma_f32 v[130:131], v[112:113], v[136:137], v[130:131]
	v_pk_fma_f32 v[102:103], v[110:111], v[134:135], v[102:103]
	v_pk_mul_f32 v[186:187], v[184:185], s[98:99] op_sel_hi:[1,0]
	v_pk_mul_f32 v[198:199], v[188:189], s[98:99] op_sel_hi:[1,0]
	v_exp_f32_e32 v186, v186
	v_exp_f32_e32 v187, v187
	v_exp_f32_e32 v198, v198
	v_exp_f32_e32 v199, v199
	v_pk_add_f32 v[186:187], v[186:187], 1.0 op_sel_hi:[1,0]
	v_pk_add_f32 v[198:199], v[198:199], 1.0 op_sel_hi:[1,0]
	v_rcp_f32_e32 v186, v186
	v_rcp_f32_e32 v187, v187
	v_rcp_f32_e32 v198, v198
	v_rcp_f32_e32 v199, v199
	v_pk_mul_f32 v[150:151], v[184:185], v[186:187]
	v_pk_mul_f32 v[156:157], v[188:189], v[198:199]
	v_pk_fma_f32 v[100:101], v[100:101], v[108:109], v[130:131]
	v_pk_fma_f32 v[98:99], v[98:99], v[106:107], v[102:103]
	v_pk_mul_f32 v[100:101], v[156:157], v[100:101]
	v_pk_mul_f32 v[98:99], v[150:151], v[98:99]
	v_cvt_pk_bf16_f32 v98, v98, v99
	v_cvt_pk_bf16_f32 v99, v100, v101
	v_mad_i64_i32 v[100:101], s[0:1], v174, s46, v[104:105]
	v_lshl_add_u64 v[100:101], v[100:101], 0, v[132:133]
	global_store_dwordx2 v[100:101], v[98:99], off
	s_nop 1
	s_nop 1
	v_mov_b32_dpp v98, v154 row_ror:2 row_mask:0xf bank_mask:0xf
	s_nop 1
	v_mov_b32_dpp v99, v155 row_ror:2 row_mask:0xf bank_mask:0xf
	s_nop 1
	v_mov_b32_dpp v100, v152 row_ror:2 row_mask:0xf bank_mask:0xf
	s_nop 1
	v_mov_b32_dpp v101, v153 row_ror:2 row_mask:0xf bank_mask:0xf
	v_mov_b32_dpp v102, v154 row_ror:1 row_mask:0xf bank_mask:0xf
	v_mov_b32_dpp v103, v155 row_ror:1 row_mask:0xf bank_mask:0xf
	v_mov_b32_dpp v130, v152 row_ror:1 row_mask:0xf bank_mask:0xf
	v_mov_b32_dpp v131, v153 row_ror:1 row_mask:0xf bank_mask:0xf
	v_cndmask_b32_e32 v98, v158, v98, vcc
	v_cndmask_b32_e32 v99, v170, v99, vcc
	v_cndmask_b32_e32 v100, v172, v100, vcc
	v_cndmask_b32_e32 v101, v180, v101, vcc
	v_cndmask_b32_e64 v102, v102, v0, s[42:43]
	v_cndmask_b32_e64 v103, v103, v159, s[42:43]
	v_cndmask_b32_e64 v130, v130, v171, s[42:43]
	v_cndmask_b32_e64 v131, v131, v173, s[42:43]
	v_pk_fma_f32 v[98:99], v[114:115], v[98:99], v[118:119]
	v_pk_fma_f32 v[100:101], v[116:117], v[100:101], v[120:121]
	v_pk_fma_f32 v[98:99], v[110:111], v[102:103], v[98:99]
	v_pk_fma_f32 v[100:101], v[112:113], v[130:131], v[100:101]
	v_pk_mul_f32 v[126:127], v[122:123], s[98:99] op_sel_hi:[1,0]
	v_pk_mul_f32 v[128:129], v[124:125], s[98:99] op_sel_hi:[1,0]
	v_exp_f32_e32 v126, v126
	v_exp_f32_e32 v127, v127
	v_exp_f32_e32 v128, v128
	v_exp_f32_e32 v129, v129
	v_pk_add_f32 v[126:127], v[126:127], 1.0 op_sel_hi:[1,0]
	v_pk_add_f32 v[128:129], v[128:129], 1.0 op_sel_hi:[1,0]
	v_rcp_f32_e32 v126, v126
	v_rcp_f32_e32 v127, v127
	v_rcp_f32_e32 v128, v128
	v_rcp_f32_e32 v129, v129
	v_pk_mul_f32 v[122:123], v[122:123], v[126:127]
	v_pk_mul_f32 v[124:125], v[124:125], v[128:129]
	v_pk_fma_f32 v[98:99], v[154:155], v[106:107], v[98:99]
	v_pk_fma_f32 v[100:101], v[152:153], v[108:109], v[100:101]
	v_pk_mul_f32 v[98:99], v[122:123], v[98:99]
	v_pk_mul_f32 v[100:101], v[124:125], v[100:101]
	v_cvt_pk_bf16_f32 v98, v98, v99
	s_nop 0
	v_cvt_pk_bf16_f32 v99, v100, v101
	v_mad_i64_i32 v[100:101], s[0:1], v175, s46, v[104:105]
	v_lshl_add_u64 v[100:101], v[100:101], 0, v[132:133]
	global_store_dwordx2 v[100:101], v[98:99], off
	s_add_i32 s0, s6, 2
	v_and_b32_e32 v129, 15, v226
	v_or_b32_e32 v106, s4, v129
	v_ashrrev_i32_e32 v107, 31, v106
	v_lshl_add_u64 v[104:105], v[106:107], 3, s[38:39]
	global_load_dwordx2 v[108:109], v[104:105], off offset:1024
	global_load_dwordx2 v[102:103], v[104:105], off offset:1152
	global_load_dwordx2 v[100:101], v[104:105], off offset:1280
	s_nop 0
	global_load_dwordx2 v[104:105], v[104:105], off offset:1408
	v_ashrrev_i32_e32 v0, 1, v226
	v_and_b32_e32 v0, -8, v0
	v_add_u32_e32 v98, s21, v0
	s_mul_hi_i32 s1, s0, 0xb000
	s_mul_i32 s0, s0, 0xb000
	s_add_u32 s0, s18, s0
	s_addc_u32 s1, s19, s1
	s_add_u32 s78, s0, s80
	s_addc_u32 s79, s1, s81
	s_waitcnt vmcnt(3)
	v_ffbh_u32_e32 v0, v109
	v_min_u32_e32 v0, 32, v0
	v_lshlrev_b64 v[108:109], v0, v[108:109]
	v_min_u32_e32 v99, 1, v108
	v_or_b32_e32 v99, v109, v99
	v_cvt_f32_u32_e32 v99, v99
	v_sub_u32_e32 v0, 32, v0
	v_ldexp_f32 v0, v99, v0
	v_mul_f32_e32 v0, 0x33800000, v0
	v_fmamk_f32 v0, v0, 0x3a800000, v210
	s_nop 0
	v_rsq_f32_e32 v0, v0
	s_nop 0
	s_nop 0
	v_ashrrev_i32_e32 v99, 31, v98
	v_pk_mul_f32 v[118:119], v[96:97], v[0:1] op_sel_hi:[1,0]
	v_pk_mul_f32 v[116:117], v[94:95], v[0:1] op_sel_hi:[1,0]
	v_pk_mul_f32 v[112:113], v[92:93], v[0:1] op_sel_hi:[1,0]
	v_pk_mul_f32 v[114:115], v[90:91], v[0:1] op_sel_hi:[1,0]
	v_lshl_add_u64 v[90:91], v[98:99], 1, s[78:79]
	v_cmp_gt_u32_e32 vcc, 2, v129
	s_and_saveexec_b64 s[0:1], vcc
	s_cbranch_execz .LBB0_117
	v_mul_u32_u24_e32 v0, 0x1600, v129
	v_lshlrev_b32_e32 v0, 1, v0
	v_cvt_pk_bf16_f32 v92, v116, v117
	v_cvt_pk_bf16_f32 v93, v118, v119
	v_lshl_add_u64 v[96:97], v[90:91], 0, v[0:1]
	v_cvt_pk_bf16_f32 v94, v114, v115
	v_cvt_pk_bf16_f32 v95, v112, v113
	global_store_dwordx2 v[96:97], v[92:93], off
	global_store_dwordx2 v[96:97], v[94:95], off offset:256

.LBB0_119:
	s_or_b64 exec, exec, s[0:1]
	v_ffbh_u32_e32 v0, v103
	v_min_u32_e32 v0, 32, v0
	v_lshlrev_b64 v[82:83], v0, v[102:103]
	v_min_u32_e32 v82, 1, v82
	v_or_b32_e32 v82, v83, v82
	v_cvt_f32_u32_e32 v82, v82
	v_sub_u32_e32 v0, 32, v0
	v_add_u32_e32 v126, s5, v98
	v_ldexp_f32 v0, v82, v0
	v_mul_f32_e32 v0, 0x33800000, v0
	v_fmamk_f32 v0, v0, 0x3a800000, v210
	s_nop 0
	v_rsq_f32_e32 v0, v0
	s_nop 0
	s_nop 0
	v_mov_b32_e32 v124, v0
	v_ffbh_u32_e32 v0, v101
	v_min_u32_e32 v0, 32, v0
	v_pk_mul_f32 v[132:133], v[78:79], v[124:125] op_sel_hi:[1,0]
	v_lshlrev_b64 v[78:79], v0, v[100:101]
	v_min_u32_e32 v78, 1, v78
	v_or_b32_e32 v78, v79, v78
	v_cvt_f32_u32_e32 v78, v78
	v_sub_u32_e32 v0, 32, v0
	v_pk_mul_f32 v[130:131], v[80:81], v[124:125] op_sel_hi:[1,0]
	v_ldexp_f32 v0, v78, v0
	v_mul_f32_e32 v0, 0x33800000, v0
	v_fmamk_f32 v0, v0, 0x3a800000, v210
	s_nop 0
	v_rsq_f32_e32 v0, v0
	s_nop 0
	s_nop 0
	v_mov_b32_e32 v128, v0
	v_pk_mul_f32 v[134:135], v[76:77], v[128:129] op_sel_hi:[1,0]
	v_pk_mul_f32 v[156:157], v[74:75], v[128:129] op_sel_hi:[1,0]
	v_ashrrev_i32_e32 v127, 31, v126
	v_lshlrev_b64 v[86:87], 2, v[126:127]
	v_lshl_add_u64 v[74:75], s[44:45], 0, v[86:87]
	v_lshl_add_u64 v[76:77], s[60:61], 0, v[86:87]
	global_load_dwordx4 v[90:93], v[74:75], off
	global_load_dwordx4 v[94:97], v[76:77], off
	v_lshl_add_u64 v[74:75], s[2:3], 0, v[86:87]
	global_load_dwordx4 v[98:101], v[74:75], off
	v_lshl_add_u64 v[74:75], s[48:49], 0, v[86:87]
	global_load_dwordx4 v[102:105], v[74:75], off
	s_nop 1
	v_cmp_lt_u32_e32 vcc, 1, v129
	v_mov_b32_dpp v174, v116 row_ror:1 row_mask:0xf bank_mask:0xf
	v_mov_b32_dpp v172, v116 row_ror:2 row_mask:0xf bank_mask:0xf
	v_mov_b32_dpp v175, v117 row_ror:1 row_mask:0xf bank_mask:0xf
	v_mov_b32_dpp v173, v117 row_ror:2 row_mask:0xf bank_mask:0xf
	v_mov_b32_dpp v170, v118 row_ror:1 row_mask:0xf bank_mask:0xf
	v_mov_b32_dpp v158, v118 row_ror:2 row_mask:0xf bank_mask:0xf
	v_mov_b32_dpp v171, v119 row_ror:1 row_mask:0xf bank_mask:0xf
	v_mov_b32_dpp v159, v119 row_ror:2 row_mask:0xf bank_mask:0xf
	v_mov_b32_dpp v191, v132 row_ror:1 row_mask:0xf bank_mask:0xf
	v_mov_b32_dpp v190, v132 row_ror:2 row_mask:0xf bank_mask:0xf
	v_mov_b32_dpp v195, v133 row_ror:1 row_mask:0xf bank_mask:0xf
	v_mov_b32_dpp v194, v133 row_ror:2 row_mask:0xf bank_mask:0xf
	v_mov_b32_dpp v179, v130 row_ror:1 row_mask:0xf bank_mask:0xf
	v_mov_b32_dpp v178, v130 row_ror:2 row_mask:0xf bank_mask:0xf
	v_mov_b32_dpp v185, v131 row_ror:1 row_mask:0xf bank_mask:0xf
	v_mov_b32_dpp v183, v131 row_ror:2 row_mask:0xf bank_mask:0xf
	v_mov_b32_dpp v184, v156 row_ror:1 row_mask:0xf bank_mask:0xf
	v_mov_b32_dpp v181, v156 row_ror:2 row_mask:0xf bank_mask:0xf
	v_mov_b32_dpp v189, v157 row_ror:1 row_mask:0xf bank_mask:0xf
	v_mov_b32_dpp v187, v157 row_ror:2 row_mask:0xf bank_mask:0xf
	v_mov_b32_dpp v107, v134 row_ror:1 row_mask:0xf bank_mask:0xf
	v_mov_b32_dpp v0, v134 row_ror:2 row_mask:0xf bank_mask:0xf
	v_mov_b32_dpp v177, v135 row_ror:1 row_mask:0xf bank_mask:0xf
	v_mov_b32_dpp v176, v135 row_ror:2 row_mask:0xf bank_mask:0xf
	v_mov_b32_dpp v193, v122 row_ror:1 row_mask:0xf bank_mask:0xf
	v_mov_b32_dpp v192, v122 row_ror:2 row_mask:0xf bank_mask:0xf
	v_mov_b32_dpp v197, v123 row_ror:1 row_mask:0xf bank_mask:0xf
	v_mov_b32_dpp v196, v123 row_ror:2 row_mask:0xf bank_mask:0xf
	v_mov_b32_dpp v182, v120 row_ror:1 row_mask:0xf bank_mask:0xf
	v_mov_b32_dpp v180, v120 row_ror:2 row_mask:0xf bank_mask:0xf
	v_mov_b32_dpp v188, v121 row_ror:1 row_mask:0xf bank_mask:0xf
	v_mov_b32_dpp v186, v121 row_ror:2 row_mask:0xf bank_mask:0xf
	v_lshl_add_u64 v[74:75], s[96:97], 0, v[86:87]
	v_lshl_add_u64 v[76:77], s[62:63], 0, v[86:87]
	global_load_dwordx4 v[82:85], v[74:75], off
	global_load_dwordx4 v[78:81], v[76:77], off
	v_lshl_add_u64 v[74:75], s[64:65], 0, v[86:87]
	v_lshl_add_u64 v[86:87], s[66:67], 0, v[86:87]
	global_load_dwordx4 v[74:77], v[74:75], off
	s_nop 1
	global_load_dwordx4 v[86:89], v[86:87], off
	s_nop 1
	v_mov_b32_dpp v136, v114 row_ror:1 row_mask:0xf bank_mask:0xf
	v_mov_b32_dpp v152, v114 row_ror:2 row_mask:0xf bank_mask:0xf
	v_mov_b32_dpp v137, v115 row_ror:1 row_mask:0xf bank_mask:0xf
	v_mov_b32_dpp v153, v115 row_ror:2 row_mask:0xf bank_mask:0xf
	v_mov_b32_dpp v150, v112 row_ror:1 row_mask:0xf bank_mask:0xf
	v_mov_b32_dpp v154, v112 row_ror:2 row_mask:0xf bank_mask:0xf
	v_mov_b32_dpp v151, v113 row_ror:1 row_mask:0xf bank_mask:0xf
	v_mov_b32_dpp v155, v113 row_ror:2 row_mask:0xf bank_mask:0xf
	s_and_saveexec_b64 s[0:1], vcc
	s_cbranch_execz .Lcg_skip1
	s_waitcnt vmcnt(4)
	v_pk_fma_f32 v[198:199], v[92:93], v[158:159], v[104:105]
	s_nop 0
	v_pk_fma_f32 v[198:199], v[96:97], v[170:171], v[198:199]
	s_nop 0
	v_pk_fma_f32 v[118:119], v[118:119], v[100:101], v[198:199]
	v_pk_fma_f32 v[198:199], v[90:91], v[172:173], v[102:103]
	v_pk_fma_f32 v[198:199], v[94:95], v[174:175], v[198:199]
	v_pk_fma_f32 v[116:117], v[116:117], v[98:99], v[198:199]
	v_add_u32_e32 v125, 0x80, v106
	v_pk_mul_f32 v[198:199], v[116:117], s[98:99] op_sel_hi:[1,0]
	v_pk_mul_f32 v[200:201], v[118:119], s[98:99] op_sel_hi:[1,0]
	v_exp_f32_e32 v198, v198
	v_exp_f32_e32 v199, v199
	v_exp_f32_e32 v200, v200
	v_exp_f32_e32 v201, v201
	v_pk_add_f32 v[198:199], v[198:199], 1.0 op_sel_hi:[1,0]
	v_pk_add_f32 v[200:201], v[200:201], 1.0 op_sel_hi:[1,0]
	v_rcp_f32_e32 v198, v198
	v_rcp_f32_e32 v199, v199
	v_rcp_f32_e32 v200, v200
	v_rcp_f32_e32 v201, v201
	v_pk_mul_f32 v[116:117], v[116:117], v[198:199]
	v_pk_mul_f32 v[118:119], v[118:119], v[200:201]
	s_waitcnt vmcnt(0)
	v_pk_fma_f32 v[198:199], v[84:85], v[154:155], v[88:89]
	v_pk_fma_f32 v[200:201], v[82:83], v[152:153], v[86:87]
	v_pk_fma_f32 v[198:199], v[80:81], v[150:151], v[198:199]
	v_pk_fma_f32 v[200:201], v[78:79], v[136:137], v[200:201]
	v_pk_fma_f32 v[112:113], v[112:113], v[76:77], v[198:199]
	v_pk_fma_f32 v[114:115], v[114:115], v[74:75], v[200:201]
	v_pk_mul_f32 v[112:113], v[118:119], v[112:113]
	v_pk_mul_f32 v[114:115], v[116:117], v[114:115]
	s_nop 0
	v_cvt_pk_bf16_f32 v114, v114, v115
	v_cvt_pk_bf16_f32 v115, v112, v113
	v_mov_b64_e32 v[112:113], s[36:37]
	v_mad_i64_i32 v[112:113], s[6:7], v125, s46, v[112:113]
	v_lshl_add_u64 v[112:113], v[126:127], 1, v[112:113]
	global_store_dwordx2 v[112:113], v[114:115], off
.LBB0_121:
	s_or_b64 exec, exec, s[0:1]
	v_cmp_eq_u32_e64 s[42:43], 0, v129
	v_cndmask_b32_e32 v115, v173, v194, vcc
	v_cndmask_b32_e32 v114, v172, v190, vcc
	v_cndmask_b32_e64 v113, v195, v175, s[42:43]
	v_cndmask_b32_e64 v112, v191, v174, s[42:43]
	s_waitcnt vmcnt(4)
	v_pk_fma_f32 v[114:115], v[90:91], v[114:115], v[102:103]
	v_cndmask_b32_e32 v119, v159, v183, vcc
	v_cndmask_b32_e32 v118, v158, v178, vcc
	v_pk_fma_f32 v[112:113], v[94:95], v[112:113], v[114:115]
	v_cndmask_b32_e64 v117, v185, v171, s[42:43]
	v_cndmask_b32_e64 v116, v179, v170, s[42:43]
	v_pk_fma_f32 v[118:119], v[92:93], v[118:119], v[104:105]
	v_pk_fma_f32 v[112:113], v[132:133], v[98:99], v[112:113]
	v_pk_fma_f32 v[116:117], v[96:97], v[116:117], v[118:119]
	v_cndmask_b32_e32 v133, v194, v187, vcc
	v_cndmask_b32_e32 v132, v190, v181, vcc
	v_pk_fma_f32 v[116:117], v[130:131], v[100:101], v[116:117]
	v_cndmask_b32_e64 v131, v189, v195, s[42:43]
	v_cndmask_b32_e64 v130, v184, v191, s[42:43]
	v_pk_fma_f32 v[132:133], v[90:91], v[132:133], v[102:103]
	v_cndmask_b32_e32 v159, v183, v176, vcc
	v_pk_fma_f32 v[130:131], v[94:95], v[130:131], v[132:133]
	v_cndmask_b32_e32 v158, v178, v0, vcc
	v_pk_fma_f32 v[130:131], v[156:157], v[98:99], v[130:131]
	v_cndmask_b32_e64 v157, v177, v185, s[42:43]
	v_cndmask_b32_e64 v156, v107, v179, s[42:43]
	v_pk_fma_f32 v[158:159], v[92:93], v[158:159], v[104:105]
	v_cndmask_b32_e32 v171, v187, v196, vcc
	v_cndmask_b32_e32 v170, v181, v192, vcc
	v_pk_fma_f32 v[156:157], v[96:97], v[156:157], v[158:159]
	v_cndmask_b32_e64 v159, v197, v189, s[42:43]
	v_cndmask_b32_e64 v158, v193, v184, s[42:43]
	v_pk_fma_f32 v[90:91], v[90:91], v[170:171], v[102:103]
	v_cndmask_b32_e32 v103, v176, v186, vcc
	v_pk_fma_f32 v[90:91], v[94:95], v[158:159], v[90:91]
	v_cndmask_b32_e32 v102, v0, v180, vcc
	v_pk_fma_f32 v[90:91], v[122:123], v[98:99], v[90:91]
	v_cndmask_b32_e64 v99, v188, v177, s[42:43]
	v_cndmask_b32_e64 v98, v182, v107, s[42:43]
	v_pk_fma_f32 v[92:93], v[92:93], v[102:103], v[104:105]
	v_pk_fma_f32 v[92:93], v[96:97], v[98:99], v[92:93]
	v_mov_b32_e32 v125, v124
	v_pk_fma_f32 v[92:93], v[120:121], v[100:101], v[92:93]
	v_mov_b32_e32 v129, v128
	v_mov_b32_e32 v98, v124
	v_mov_b32_e32 v99, v124
	v_pk_mul_f32 v[72:73], v[72:73], v[98:99]
	v_pk_mul_f32 v[70:71], v[70:71], v[124:125]
	v_pk_mul_f32 v[66:67], v[66:67], v[128:129]
	s_nop 1
	v_mov_b32_e32 v98, v128
	v_mov_b32_e32 v99, v128
	s_nop 1
	v_mov_b32_dpp v123, v70 row_ror:2 row_mask:0xf bank_mask:0xf
	s_nop 1
	v_mov_b32_dpp v125, v71 row_ror:2 row_mask:0xf bank_mask:0xf
	s_nop 1
	v_mov_b32_dpp v129, v72 row_ror:2 row_mask:0xf bank_mask:0xf
	s_nop 1
	v_mov_b32_dpp v159, v73 row_ror:2 row_mask:0xf bank_mask:0xf
	v_pk_fma_f32 v[134:135], v[134:135], v[100:101], v[156:157]
	v_pk_mul_f32 v[68:69], v[68:69], v[98:99]
	v_mov_b32_dpp v122, v70 row_ror:1 row_mask:0xf bank_mask:0xf
	v_mov_b32_dpp v124, v71 row_ror:1 row_mask:0xf bank_mask:0xf
	v_mov_b32_dpp v128, v72 row_ror:1 row_mask:0xf bank_mask:0xf
	v_mov_b32_dpp v158, v73 row_ror:1 row_mask:0xf bank_mask:0xf
	v_cndmask_b32_e32 v98, v152, v123, vcc
	v_cndmask_b32_e32 v99, v153, v125, vcc
	v_cndmask_b32_e32 v100, v154, v129, vcc
	v_cndmask_b32_e32 v101, v155, v159, vcc
	v_cndmask_b32_e64 v102, v122, v136, s[42:43]
	v_cndmask_b32_e64 v103, v124, v137, s[42:43]
	v_cndmask_b32_e64 v104, v128, v150, s[42:43]
	v_cndmask_b32_e64 v105, v158, v151, s[42:43]
	s_waitcnt vmcnt(1)
	v_pk_fma_f32 v[100:101], v[84:85], v[100:101], v[88:89]
	v_pk_fma_f32 v[98:99], v[82:83], v[98:99], v[86:87]
	v_pk_fma_f32 v[100:101], v[80:81], v[104:105], v[100:101]
	v_pk_fma_f32 v[98:99], v[78:79], v[102:103], v[98:99]
	v_add_u32_e32 v0, 0x90, v106
	v_add_u32_e32 v120, 0xa0, v106
	v_add_u32_e32 v121, 0xb0, v106
	v_pk_mul_f32 v[114:115], v[112:113], s[98:99] op_sel_hi:[1,0]
	v_pk_mul_f32 v[118:119], v[116:117], s[98:99] op_sel_hi:[1,0]
	v_exp_f32_e32 v114, v114
	v_exp_f32_e32 v115, v115
	v_exp_f32_e32 v118, v118
	v_exp_f32_e32 v119, v119
	v_pk_add_f32 v[114:115], v[114:115], 1.0 op_sel_hi:[1,0]
	v_pk_add_f32 v[118:119], v[118:119], 1.0 op_sel_hi:[1,0]
	v_rcp_f32_e32 v114, v114
	v_rcp_f32_e32 v115, v115
	v_rcp_f32_e32 v118, v118
	v_rcp_f32_e32 v119, v119
	v_pk_mul_f32 v[106:107], v[112:113], v[114:115]
	v_pk_mul_f32 v[112:113], v[116:117], v[118:119]
	v_pk_fma_f32 v[72:73], v[72:73], v[76:77], v[100:101]
	v_pk_fma_f32 v[70:71], v[70:71], v[74:75], v[98:99]
	v_pk_mul_f32 v[72:73], v[112:113], v[72:73]
	v_pk_mul_f32 v[70:71], v[106:107], v[70:71]
	v_cvt_pk_bf16_f32 v70, v70, v71
	v_cvt_pk_bf16_f32 v71, v72, v73
	v_mov_b64_e32 v[72:73], s[36:37]
	v_mad_i64_i32 v[98:99], s[0:1], v0, s46, v[72:73]
	v_lshlrev_b64 v[100:101], 1, v[126:127]
	s_nop 1
	v_lshl_add_u64 v[98:99], v[98:99], 0, v[100:101]
	s_nop 1
	v_mov_b32_dpp v114, v66 row_ror:2 row_mask:0xf bank_mask:0xf
	s_nop 1
	v_mov_b32_dpp v116, v67 row_ror:2 row_mask:0xf bank_mask:0xf
	s_nop 1
	v_mov_b32_dpp v118, v68 row_ror:2 row_mask:0xf bank_mask:0xf
	s_nop 1
	v_mov_b32_dpp v126, v69 row_ror:2 row_mask:0xf bank_mask:0xf
	global_store_dwordx2 v[98:99], v[70:71], off
	v_mov_b32_dpp v0, v66 row_ror:1 row_mask:0xf bank_mask:0xf
	v_mov_b32_dpp v115, v67 row_ror:1 row_mask:0xf bank_mask:0xf
	v_mov_b32_dpp v117, v68 row_ror:1 row_mask:0xf bank_mask:0xf
	v_mov_b32_dpp v119, v69 row_ror:1 row_mask:0xf bank_mask:0xf
	v_cndmask_b32_e32 v70, v123, v114, vcc
	v_cndmask_b32_e32 v71, v125, v116, vcc
	v_cndmask_b32_e32 v98, v129, v118, vcc
	v_cndmask_b32_e32 v99, v159, v126, vcc
	v_cndmask_b32_e64 v102, v0, v122, s[42:43]
	v_cndmask_b32_e64 v103, v115, v124, s[42:43]
	v_cndmask_b32_e64 v104, v117, v128, s[42:43]
	v_cndmask_b32_e64 v105, v119, v158, s[42:43]
	v_pk_fma_f32 v[98:99], v[84:85], v[98:99], v[88:89]
	v_pk_fma_f32 v[70:71], v[82:83], v[70:71], v[86:87]
	v_pk_fma_f32 v[98:99], v[80:81], v[104:105], v[98:99]
	v_pk_fma_f32 v[70:71], v[78:79], v[102:103], v[70:71]
	v_pk_mul_f32 v[132:133], v[130:131], s[98:99] op_sel_hi:[1,0]
	v_pk_mul_f32 v[156:157], v[134:135], s[98:99] op_sel_hi:[1,0]
	v_exp_f32_e32 v132, v132
	v_exp_f32_e32 v133, v133
	v_exp_f32_e32 v156, v156
	v_exp_f32_e32 v157, v157
	v_pk_add_f32 v[132:133], v[132:133], 1.0 op_sel_hi:[1,0]
	v_pk_add_f32 v[156:157], v[156:157], 1.0 op_sel_hi:[1,0]
	v_rcp_f32_e32 v132, v132
	v_rcp_f32_e32 v133, v133
	v_rcp_f32_e32 v156, v156
	v_rcp_f32_e32 v157, v157
	v_pk_mul_f32 v[106:107], v[130:131], v[132:133]
	v_pk_mul_f32 v[112:113], v[134:135], v[156:157]
	v_pk_fma_f32 v[68:69], v[68:69], v[76:77], v[98:99]
	v_pk_fma_f32 v[66:67], v[66:67], v[74:75], v[70:71]
	v_pk_mul_f32 v[68:69], v[112:113], v[68:69]
	v_pk_mul_f32 v[66:67], v[106:107], v[66:67]
	v_cvt_pk_bf16_f32 v66, v66, v67
	v_cvt_pk_bf16_f32 v67, v68, v69
	v_mad_i64_i32 v[68:69], s[0:1], v120, s46, v[72:73]
	v_lshl_add_u64 v[68:69], v[68:69], 0, v[100:101]
	global_store_dwordx2 v[68:69], v[66:67], off
	s_nop 1
	s_nop 1
	v_mov_b32_dpp v66, v110 row_ror:2 row_mask:0xf bank_mask:0xf
	s_nop 1
	v_mov_b32_dpp v67, v111 row_ror:2 row_mask:0xf bank_mask:0xf
	s_nop 1
	v_mov_b32_dpp v68, v108 row_ror:2 row_mask:0xf bank_mask:0xf
	s_nop 1
	v_mov_b32_dpp v69, v109 row_ror:2 row_mask:0xf bank_mask:0xf
	v_mov_b32_dpp v70, v110 row_ror:1 row_mask:0xf bank_mask:0xf
	v_mov_b32_dpp v71, v111 row_ror:1 row_mask:0xf bank_mask:0xf
	v_mov_b32_dpp v98, v108 row_ror:1 row_mask:0xf bank_mask:0xf
	v_mov_b32_dpp v99, v109 row_ror:1 row_mask:0xf bank_mask:0xf
	v_cndmask_b32_e32 v66, v114, v66, vcc
	v_cndmask_b32_e32 v67, v116, v67, vcc
	v_cndmask_b32_e32 v68, v118, v68, vcc
	v_cndmask_b32_e32 v69, v126, v69, vcc
	v_cndmask_b32_e64 v70, v70, v0, s[42:43]
	v_cndmask_b32_e64 v71, v71, v115, s[42:43]
	v_cndmask_b32_e64 v98, v98, v117, s[42:43]
	v_cndmask_b32_e64 v99, v99, v119, s[42:43]
	v_pk_fma_f32 v[66:67], v[82:83], v[66:67], v[86:87]
	v_pk_fma_f32 v[68:69], v[84:85], v[68:69], v[88:89]
	v_pk_fma_f32 v[66:67], v[78:79], v[70:71], v[66:67]
	v_pk_fma_f32 v[68:69], v[80:81], v[98:99], v[68:69]
	v_pk_mul_f32 v[94:95], v[90:91], s[98:99] op_sel_hi:[1,0]
	v_pk_mul_f32 v[96:97], v[92:93], s[98:99] op_sel_hi:[1,0]
	v_exp_f32_e32 v94, v94
	v_exp_f32_e32 v95, v95
	v_exp_f32_e32 v96, v96
	v_exp_f32_e32 v97, v97
	v_pk_add_f32 v[94:95], v[94:95], 1.0 op_sel_hi:[1,0]
	v_pk_add_f32 v[96:97], v[96:97], 1.0 op_sel_hi:[1,0]
	v_rcp_f32_e32 v94, v94
	v_rcp_f32_e32 v95, v95
	v_rcp_f32_e32 v96, v96
	v_rcp_f32_e32 v97, v97
	v_pk_mul_f32 v[90:91], v[90:91], v[94:95]
	v_pk_mul_f32 v[92:93], v[92:93], v[96:97]
	v_pk_fma_f32 v[66:67], v[110:111], v[74:75], v[66:67]
	v_pk_fma_f32 v[68:69], v[108:109], v[76:77], v[68:69]
	v_pk_mul_f32 v[66:67], v[90:91], v[66:67]
	v_pk_mul_f32 v[68:69], v[92:93], v[68:69]
	v_cvt_pk_bf16_f32 v66, v66, v67
	s_nop 0
	v_cvt_pk_bf16_f32 v67, v68, v69
	v_mad_i64_i32 v[68:69], s[0:1], v121, s46, v[72:73]
	v_lshl_add_u64 v[68:69], v[68:69], 0, v[100:101]
	global_store_dwordx2 v[68:69], v[66:67], off
	s_nop 0
	v_and_b32_e32 v97, 15, v226
	v_or_b32_e32 v74, s4, v97
	v_ashrrev_i32_e32 v75, 31, v74
	v_lshl_add_u64 v[72:73], v[74:75], 3, s[38:39]
	global_load_dwordx2 v[76:77], v[72:73], off
	global_load_dwordx2 v[70:71], v[72:73], off offset:128
	global_load_dwordx2 v[68:69], v[72:73], off offset:256
	s_nop 0
	global_load_dwordx2 v[72:73], v[72:73], off offset:384
	v_ashrrev_i32_e32 v0, 1, v226
	v_and_b32_e32 v0, -8, v0
	v_add_u32_e32 v66, s21, v0
	s_waitcnt vmcnt(3)
	v_ffbh_u32_e32 v0, v77
	v_min_u32_e32 v0, 32, v0
	v_lshlrev_b64 v[76:77], v0, v[76:77]
	v_min_u32_e32 v67, 1, v76
	v_or_b32_e32 v67, v77, v67
	v_cvt_f32_u32_e32 v67, v67
	v_sub_u32_e32 v0, 32, v0
	v_ldexp_f32 v0, v67, v0
	v_mul_f32_e32 v0, 0x33800000, v0
	v_fmamk_f32 v0, v0, 0x3a800000, v210
	s_nop 0
	v_rsq_f32_e32 v0, v0
	s_nop 0
	s_nop 0
	v_ashrrev_i32_e32 v67, 31, v66
	v_pk_mul_f32 v[92:93], v[64:65], v[0:1] op_sel_hi:[1,0]
	v_pk_mul_f32 v[90:91], v[62:63], v[0:1] op_sel_hi:[1,0]
	v_pk_mul_f32 v[86:87], v[60:61], v[0:1] op_sel_hi:[1,0]
	v_pk_mul_f32 v[88:89], v[58:59], v[0:1] op_sel_hi:[1,0]
	v_lshl_add_u64 v[58:59], v[66:67], 1, s[76:77]
	v_cmp_gt_u32_e32 vcc, 2, v97
	s_and_saveexec_b64 s[0:1], vcc
	s_cbranch_execz .LBB0_123
	v_mul_u32_u24_e32 v0, 0x1600, v97
	v_lshlrev_b32_e32 v0, 1, v0
	v_cvt_pk_bf16_f32 v60, v90, v91
	v_cvt_pk_bf16_f32 v61, v92, v93
	v_lshl_add_u64 v[64:65], v[58:59], 0, v[0:1]
	v_cvt_pk_bf16_f32 v62, v88, v89
	v_cvt_pk_bf16_f32 v63, v86, v87
	global_store_dwordx2 v[64:65], v[60:61], off offset:8
	global_store_dwordx2 v[64:65], v[62:63], off offset:264

.LBB0_125:
	s_or_b64 exec, exec, s[0:1]
	v_ffbh_u32_e32 v0, v71
	v_min_u32_e32 v0, 32, v0
	v_lshlrev_b64 v[50:51], v0, v[70:71]
	v_min_u32_e32 v50, 1, v50
	v_or_b32_e32 v50, v51, v50
	v_cvt_f32_u32_e32 v50, v50
	v_sub_u32_e32 v0, 32, v0
	s_or_b32 s5, s5, 4
	v_add_u32_e32 v94, s5, v66
	v_ldexp_f32 v0, v50, v0
	v_mul_f32_e32 v0, 0x33800000, v0
	v_fmamk_f32 v0, v0, 0x3a800000, v210
	s_nop 0
	v_rsq_f32_e32 v0, v0
	s_nop 0
	s_nop 0
	v_mov_b32_e32 v84, v0
	v_ffbh_u32_e32 v0, v69
	v_min_u32_e32 v0, 32, v0
	v_pk_mul_f32 v[100:101], v[46:47], v[84:85] op_sel_hi:[1,0]
	v_lshlrev_b64 v[46:47], v0, v[68:69]
	v_min_u32_e32 v46, 1, v46
	v_or_b32_e32 v46, v47, v46
	v_cvt_f32_u32_e32 v46, v46
	v_sub_u32_e32 v0, 32, v0
	v_pk_mul_f32 v[98:99], v[48:49], v[84:85] op_sel_hi:[1,0]
	v_ldexp_f32 v0, v46, v0
	v_mul_f32_e32 v0, 0x33800000, v0
	v_fmamk_f32 v0, v0, 0x3a800000, v210
	s_nop 0
	v_rsq_f32_e32 v0, v0
	s_nop 0
	s_nop 0
	v_mov_b32_e32 v96, v0
	v_pk_mul_f32 v[102:103], v[44:45], v[96:97] op_sel_hi:[1,0]
	v_pk_mul_f32 v[112:113], v[42:43], v[96:97] op_sel_hi:[1,0]
	v_ashrrev_i32_e32 v95, 31, v94
	v_lshlrev_b64 v[54:55], 2, v[94:95]
	v_lshl_add_u64 v[42:43], s[44:45], 0, v[54:55]
	v_lshl_add_u64 v[44:45], s[60:61], 0, v[54:55]
	global_load_dwordx4 v[58:61], v[42:43], off
	global_load_dwordx4 v[62:65], v[44:45], off
	v_lshl_add_u64 v[42:43], s[2:3], 0, v[54:55]
	global_load_dwordx4 v[66:69], v[42:43], off
	v_lshl_add_u64 v[42:43], s[48:49], 0, v[54:55]
	global_load_dwordx4 v[70:73], v[42:43], off
	s_nop 1
	v_cmp_lt_u32_e32 vcc, 1, v97
	v_mov_b32_dpp v120, v90 row_ror:1 row_mask:0xf bank_mask:0xf
	v_mov_b32_dpp v118, v90 row_ror:2 row_mask:0xf bank_mask:0xf
	v_mov_b32_dpp v121, v91 row_ror:1 row_mask:0xf bank_mask:0xf
	v_mov_b32_dpp v119, v91 row_ror:2 row_mask:0xf bank_mask:0xf
	v_mov_b32_dpp v116, v92 row_ror:1 row_mask:0xf bank_mask:0xf
	v_mov_b32_dpp v114, v92 row_ror:2 row_mask:0xf bank_mask:0xf
	v_mov_b32_dpp v117, v93 row_ror:1 row_mask:0xf bank_mask:0xf
	v_mov_b32_dpp v115, v93 row_ror:2 row_mask:0xf bank_mask:0xf
	v_mov_b32_dpp v137, v100 row_ror:1 row_mask:0xf bank_mask:0xf
	v_mov_b32_dpp v136, v100 row_ror:2 row_mask:0xf bank_mask:0xf
	v_mov_b32_dpp v153, v101 row_ror:1 row_mask:0xf bank_mask:0xf
	v_mov_b32_dpp v152, v101 row_ror:2 row_mask:0xf bank_mask:0xf
	v_mov_b32_dpp v125, v98 row_ror:1 row_mask:0xf bank_mask:0xf
	v_mov_b32_dpp v124, v98 row_ror:2 row_mask:0xf bank_mask:0xf
	v_mov_b32_dpp v131, v99 row_ror:1 row_mask:0xf bank_mask:0xf
	v_mov_b32_dpp v129, v99 row_ror:2 row_mask:0xf bank_mask:0xf
	v_mov_b32_dpp v130, v112 row_ror:1 row_mask:0xf bank_mask:0xf
	v_mov_b32_dpp v127, v112 row_ror:2 row_mask:0xf bank_mask:0xf
	v_mov_b32_dpp v135, v113 row_ror:1 row_mask:0xf bank_mask:0xf
	v_mov_b32_dpp v133, v113 row_ror:2 row_mask:0xf bank_mask:0xf
	v_mov_b32_dpp v75, v102 row_ror:1 row_mask:0xf bank_mask:0xf
	v_mov_b32_dpp v0, v102 row_ror:2 row_mask:0xf bank_mask:0xf
	v_mov_b32_dpp v123, v103 row_ror:1 row_mask:0xf bank_mask:0xf
	v_mov_b32_dpp v122, v103 row_ror:2 row_mask:0xf bank_mask:0xf
	v_mov_b32_dpp v151, v82 row_ror:1 row_mask:0xf bank_mask:0xf
	v_mov_b32_dpp v150, v82 row_ror:2 row_mask:0xf bank_mask:0xf
	v_mov_b32_dpp v155, v83 row_ror:1 row_mask:0xf bank_mask:0xf
	v_mov_b32_dpp v154, v83 row_ror:2 row_mask:0xf bank_mask:0xf
	v_mov_b32_dpp v128, v80 row_ror:1 row_mask:0xf bank_mask:0xf
	v_mov_b32_dpp v126, v80 row_ror:2 row_mask:0xf bank_mask:0xf
	v_mov_b32_dpp v134, v81 row_ror:1 row_mask:0xf bank_mask:0xf
	v_mov_b32_dpp v132, v81 row_ror:2 row_mask:0xf bank_mask:0xf
	v_lshl_add_u64 v[42:43], s[96:97], 0, v[54:55]
	v_lshl_add_u64 v[44:45], s[62:63], 0, v[54:55]
	global_load_dwordx4 v[50:53], v[42:43], off
	global_load_dwordx4 v[46:49], v[44:45], off
	v_lshl_add_u64 v[42:43], s[64:65], 0, v[54:55]
	v_lshl_add_u64 v[54:55], s[66:67], 0, v[54:55]
	global_load_dwordx4 v[42:45], v[42:43], off
	s_nop 1
	global_load_dwordx4 v[54:57], v[54:55], off
	s_nop 1
	v_mov_b32_dpp v104, v88 row_ror:1 row_mask:0xf bank_mask:0xf
	v_mov_b32_dpp v108, v88 row_ror:2 row_mask:0xf bank_mask:0xf
	v_mov_b32_dpp v105, v89 row_ror:1 row_mask:0xf bank_mask:0xf
	v_mov_b32_dpp v109, v89 row_ror:2 row_mask:0xf bank_mask:0xf
	v_mov_b32_dpp v106, v86 row_ror:1 row_mask:0xf bank_mask:0xf
	v_mov_b32_dpp v110, v86 row_ror:2 row_mask:0xf bank_mask:0xf
	v_mov_b32_dpp v107, v87 row_ror:1 row_mask:0xf bank_mask:0xf
	v_mov_b32_dpp v111, v87 row_ror:2 row_mask:0xf bank_mask:0xf
	s_and_saveexec_b64 s[0:1], vcc
	s_cbranch_execz .Lcg_skip2
	s_waitcnt vmcnt(4)
	v_pk_fma_f32 v[156:157], v[60:61], v[114:115], v[72:73]
	s_nop 0
	v_pk_fma_f32 v[156:157], v[64:65], v[116:117], v[156:157]
	s_nop 0
	v_pk_fma_f32 v[92:93], v[92:93], v[68:69], v[156:157]
	v_pk_fma_f32 v[156:157], v[58:59], v[118:119], v[70:71]
	v_pk_fma_f32 v[156:157], v[62:63], v[120:121], v[156:157]
	v_pk_fma_f32 v[90:91], v[90:91], v[66:67], v[156:157]
	v_pk_mul_f32 v[156:157], v[90:91], s[98:99] op_sel_hi:[1,0]
	v_pk_mul_f32 v[158:159], v[92:93], s[98:99] op_sel_hi:[1,0]
	v_exp_f32_e32 v156, v156
	v_exp_f32_e32 v157, v157
	v_exp_f32_e32 v158, v158
	v_exp_f32_e32 v159, v159
	v_pk_add_f32 v[156:157], v[156:157], 1.0 op_sel_hi:[1,0]
	v_pk_add_f32 v[158:159], v[158:159], 1.0 op_sel_hi:[1,0]
	v_rcp_f32_e32 v156, v156
	v_rcp_f32_e32 v157, v157
	v_rcp_f32_e32 v158, v158
	v_rcp_f32_e32 v159, v159
	v_pk_mul_f32 v[90:91], v[90:91], v[156:157]
	v_pk_mul_f32 v[92:93], v[92:93], v[158:159]
	s_waitcnt vmcnt(0)
	v_pk_fma_f32 v[156:157], v[52:53], v[110:111], v[56:57]
	v_pk_fma_f32 v[158:159], v[50:51], v[108:109], v[54:55]
	v_pk_fma_f32 v[156:157], v[48:49], v[106:107], v[156:157]
	v_pk_fma_f32 v[158:159], v[46:47], v[104:105], v[158:159]
	v_pk_fma_f32 v[86:87], v[86:87], v[44:45], v[156:157]
	v_pk_fma_f32 v[88:89], v[88:89], v[42:43], v[158:159]
	v_pk_mul_f32 v[86:87], v[92:93], v[86:87]
	v_pk_mul_f32 v[88:89], v[90:91], v[88:89]
	s_nop 0
	v_cvt_pk_bf16_f32 v88, v88, v89
	v_cvt_pk_bf16_f32 v89, v86, v87
	v_mov_b64_e32 v[86:87], s[36:37]
	v_mad_i64_i32 v[86:87], s[6:7], v74, s46, v[86:87]
	v_lshl_add_u64 v[86:87], v[94:95], 1, v[86:87]
	global_store_dwordx2 v[86:87], v[88:89], off
.LBB0_127:
	s_or_b64 exec, exec, s[0:1]
	v_cmp_eq_u32_e64 s[42:43], 0, v97
	v_cndmask_b32_e32 v89, v119, v152, vcc
	v_cndmask_b32_e32 v88, v118, v136, vcc
	v_cndmask_b32_e64 v87, v153, v121, s[42:43]
	v_cndmask_b32_e64 v86, v137, v120, s[42:43]
	s_waitcnt vmcnt(4)
	v_pk_fma_f32 v[88:89], v[58:59], v[88:89], v[70:71]
	v_cndmask_b32_e32 v93, v115, v129, vcc
	v_cndmask_b32_e32 v92, v114, v124, vcc
	v_pk_fma_f32 v[86:87], v[62:63], v[86:87], v[88:89]
	v_cndmask_b32_e64 v91, v131, v117, s[42:43]
	v_cndmask_b32_e64 v90, v125, v116, s[42:43]
	v_pk_fma_f32 v[92:93], v[60:61], v[92:93], v[72:73]
	v_pk_fma_f32 v[86:87], v[100:101], v[66:67], v[86:87]
	v_pk_fma_f32 v[90:91], v[64:65], v[90:91], v[92:93]
	v_cndmask_b32_e32 v101, v152, v133, vcc
	v_cndmask_b32_e32 v100, v136, v127, vcc
	v_pk_fma_f32 v[90:91], v[98:99], v[68:69], v[90:91]
	v_cndmask_b32_e64 v99, v135, v153, s[42:43]
	v_cndmask_b32_e64 v98, v130, v137, s[42:43]
	v_pk_fma_f32 v[100:101], v[58:59], v[100:101], v[70:71]
	v_cndmask_b32_e32 v115, v129, v122, vcc
	v_pk_fma_f32 v[98:99], v[62:63], v[98:99], v[100:101]
	v_cndmask_b32_e32 v114, v124, v0, vcc
	v_pk_fma_f32 v[98:99], v[112:113], v[66:67], v[98:99]
	v_cndmask_b32_e64 v113, v123, v131, s[42:43]
	v_cndmask_b32_e64 v112, v75, v125, s[42:43]
	v_pk_fma_f32 v[114:115], v[60:61], v[114:115], v[72:73]
	v_cndmask_b32_e32 v117, v133, v154, vcc
	v_cndmask_b32_e32 v116, v127, v150, vcc
	v_pk_fma_f32 v[112:113], v[64:65], v[112:113], v[114:115]
	v_cndmask_b32_e64 v115, v155, v135, s[42:43]
	v_cndmask_b32_e64 v114, v151, v130, s[42:43]
	v_pk_fma_f32 v[58:59], v[58:59], v[116:117], v[70:71]
	v_cndmask_b32_e32 v71, v122, v132, vcc
	v_pk_fma_f32 v[58:59], v[62:63], v[114:115], v[58:59]
	v_cndmask_b32_e32 v70, v0, v126, vcc
	v_pk_fma_f32 v[58:59], v[82:83], v[66:67], v[58:59]
	v_cndmask_b32_e64 v67, v134, v123, s[42:43]
	v_cndmask_b32_e64 v66, v128, v75, s[42:43]
	v_pk_fma_f32 v[60:61], v[60:61], v[70:71], v[72:73]
	v_pk_fma_f32 v[60:61], v[64:65], v[66:67], v[60:61]
	v_mov_b32_e32 v85, v84
	v_pk_fma_f32 v[60:61], v[80:81], v[68:69], v[60:61]
	v_mov_b32_e32 v97, v96
	v_mov_b32_e32 v66, v84
	v_mov_b32_e32 v67, v84
	v_pk_mul_f32 v[40:41], v[40:41], v[66:67]
	v_pk_mul_f32 v[38:39], v[38:39], v[84:85]
	v_pk_mul_f32 v[34:35], v[34:35], v[96:97]
	s_nop 1
	v_mov_b32_e32 v66, v96
	v_mov_b32_e32 v67, v96
	s_nop 1
	v_mov_b32_dpp v85, v38 row_ror:2 row_mask:0xf bank_mask:0xf
	s_nop 1
	v_mov_b32_dpp v97, v39 row_ror:2 row_mask:0xf bank_mask:0xf
	s_nop 1
	v_mov_b32_dpp v115, v40 row_ror:2 row_mask:0xf bank_mask:0xf
	s_nop 1
	v_mov_b32_dpp v117, v41 row_ror:2 row_mask:0xf bank_mask:0xf
	v_pk_fma_f32 v[102:103], v[102:103], v[68:69], v[112:113]
	v_pk_mul_f32 v[36:37], v[36:37], v[66:67]
	v_mov_b32_dpp v84, v38 row_ror:1 row_mask:0xf bank_mask:0xf
	v_mov_b32_dpp v96, v39 row_ror:1 row_mask:0xf bank_mask:0xf
	v_mov_b32_dpp v114, v40 row_ror:1 row_mask:0xf bank_mask:0xf
	v_mov_b32_dpp v116, v41 row_ror:1 row_mask:0xf bank_mask:0xf
	v_cndmask_b32_e32 v66, v108, v85, vcc
	v_cndmask_b32_e32 v67, v109, v97, vcc
	v_cndmask_b32_e32 v68, v110, v115, vcc
	v_cndmask_b32_e32 v69, v111, v117, vcc
	v_cndmask_b32_e64 v70, v84, v104, s[42:43]
	v_cndmask_b32_e64 v71, v96, v105, s[42:43]
	v_cndmask_b32_e64 v72, v114, v106, s[42:43]
	v_cndmask_b32_e64 v73, v116, v107, s[42:43]
	s_waitcnt vmcnt(1)
	v_pk_fma_f32 v[68:69], v[52:53], v[68:69], v[56:57]
	v_pk_fma_f32 v[66:67], v[50:51], v[66:67], v[54:55]
	v_pk_fma_f32 v[68:69], v[48:49], v[72:73], v[68:69]
	v_pk_fma_f32 v[66:67], v[46:47], v[70:71], v[66:67]
	v_or_b32_e32 v0, 16, v74
	v_or_b32_e32 v82, 32, v74
	v_or_b32_e32 v83, 48, v74
	v_pk_mul_f32 v[88:89], v[86:87], s[98:99] op_sel_hi:[1,0]
	v_pk_mul_f32 v[92:93], v[90:91], s[98:99] op_sel_hi:[1,0]
	v_exp_f32_e32 v88, v88
	v_exp_f32_e32 v89, v89
	v_exp_f32_e32 v92, v92
	v_exp_f32_e32 v93, v93
	v_pk_add_f32 v[88:89], v[88:89], 1.0 op_sel_hi:[1,0]
	v_pk_add_f32 v[92:93], v[92:93], 1.0 op_sel_hi:[1,0]
	v_rcp_f32_e32 v88, v88
	v_rcp_f32_e32 v89, v89
	v_rcp_f32_e32 v92, v92
	v_rcp_f32_e32 v93, v93
	v_pk_mul_f32 v[74:75], v[86:87], v[88:89]
	v_pk_mul_f32 v[80:81], v[90:91], v[92:93]
	v_pk_fma_f32 v[40:41], v[40:41], v[44:45], v[68:69]
	v_pk_fma_f32 v[38:39], v[38:39], v[42:43], v[66:67]
	v_pk_mul_f32 v[40:41], v[80:81], v[40:41]
	v_pk_mul_f32 v[38:39], v[74:75], v[38:39]
	v_cvt_pk_bf16_f32 v38, v38, v39
	v_cvt_pk_bf16_f32 v39, v40, v41
	v_mov_b64_e32 v[40:41], s[36:37]
	v_mad_i64_i32 v[66:67], s[0:1], v0, s46, v[40:41]
	v_lshlrev_b64 v[68:69], 1, v[94:95]
	s_nop 1
	v_lshl_add_u64 v[66:67], v[66:67], 0, v[68:69]
	s_nop 1
	v_mov_b32_dpp v86, v34 row_ror:2 row_mask:0xf bank_mask:0xf
	s_nop 1
	v_mov_b32_dpp v88, v35 row_ror:2 row_mask:0xf bank_mask:0xf
	s_nop 1
	v_mov_b32_dpp v90, v36 row_ror:2 row_mask:0xf bank_mask:0xf
	s_nop 1
	v_mov_b32_dpp v92, v37 row_ror:2 row_mask:0xf bank_mask:0xf
	global_store_dwordx2 v[66:67], v[38:39], off
	v_mov_b32_dpp v0, v34 row_ror:1 row_mask:0xf bank_mask:0xf
	v_mov_b32_dpp v87, v35 row_ror:1 row_mask:0xf bank_mask:0xf
	v_mov_b32_dpp v89, v36 row_ror:1 row_mask:0xf bank_mask:0xf
	v_mov_b32_dpp v91, v37 row_ror:1 row_mask:0xf bank_mask:0xf
	v_cndmask_b32_e32 v38, v85, v86, vcc
	v_cndmask_b32_e32 v39, v97, v88, vcc
	v_cndmask_b32_e32 v66, v115, v90, vcc
	v_cndmask_b32_e32 v67, v117, v92, vcc
	v_cndmask_b32_e64 v70, v0, v84, s[42:43]
	v_cndmask_b32_e64 v71, v87, v96, s[42:43]
	v_cndmask_b32_e64 v72, v89, v114, s[42:43]
	v_cndmask_b32_e64 v73, v91, v116, s[42:43]
	v_pk_fma_f32 v[66:67], v[52:53], v[66:67], v[56:57]
	v_pk_fma_f32 v[38:39], v[50:51], v[38:39], v[54:55]
	v_pk_fma_f32 v[66:67], v[48:49], v[72:73], v[66:67]
	v_pk_fma_f32 v[38:39], v[46:47], v[70:71], v[38:39]
	v_pk_mul_f32 v[100:101], v[98:99], s[98:99] op_sel_hi:[1,0]
	v_pk_mul_f32 v[112:113], v[102:103], s[98:99] op_sel_hi:[1,0]
	v_exp_f32_e32 v100, v100
	v_exp_f32_e32 v101, v101
	v_exp_f32_e32 v112, v112
	v_exp_f32_e32 v113, v113
	v_pk_add_f32 v[100:101], v[100:101], 1.0 op_sel_hi:[1,0]
	v_pk_add_f32 v[112:113], v[112:113], 1.0 op_sel_hi:[1,0]
	v_rcp_f32_e32 v100, v100
	v_rcp_f32_e32 v101, v101
	v_rcp_f32_e32 v112, v112
	v_rcp_f32_e32 v113, v113
	v_pk_mul_f32 v[74:75], v[98:99], v[100:101]
	v_pk_mul_f32 v[80:81], v[102:103], v[112:113]
	v_pk_fma_f32 v[36:37], v[36:37], v[44:45], v[66:67]
	v_pk_fma_f32 v[34:35], v[34:35], v[42:43], v[38:39]
	v_pk_mul_f32 v[36:37], v[80:81], v[36:37]
	v_pk_mul_f32 v[34:35], v[74:75], v[34:35]
	v_cvt_pk_bf16_f32 v34, v34, v35
	v_cvt_pk_bf16_f32 v35, v36, v37
	v_mad_i64_i32 v[36:37], s[0:1], v82, s46, v[40:41]
	v_lshl_add_u64 v[36:37], v[36:37], 0, v[68:69]
	global_store_dwordx2 v[36:37], v[34:35], off
	s_nop 1
	s_nop 1
	v_mov_b32_dpp v34, v78 row_ror:2 row_mask:0xf bank_mask:0xf
	s_nop 1
	v_mov_b32_dpp v35, v79 row_ror:2 row_mask:0xf bank_mask:0xf
	s_nop 1
	v_mov_b32_dpp v36, v76 row_ror:2 row_mask:0xf bank_mask:0xf
	s_nop 1
	v_mov_b32_dpp v37, v77 row_ror:2 row_mask:0xf bank_mask:0xf
	v_mov_b32_dpp v38, v78 row_ror:1 row_mask:0xf bank_mask:0xf
	v_mov_b32_dpp v39, v79 row_ror:1 row_mask:0xf bank_mask:0xf
	v_mov_b32_dpp v66, v76 row_ror:1 row_mask:0xf bank_mask:0xf
	v_mov_b32_dpp v67, v77 row_ror:1 row_mask:0xf bank_mask:0xf
	v_cndmask_b32_e32 v34, v86, v34, vcc
	v_cndmask_b32_e32 v35, v88, v35, vcc
	v_cndmask_b32_e32 v36, v90, v36, vcc
	v_cndmask_b32_e32 v37, v92, v37, vcc
	v_cndmask_b32_e64 v38, v38, v0, s[42:43]
	v_cndmask_b32_e64 v39, v39, v87, s[42:43]
	v_cndmask_b32_e64 v66, v66, v89, s[42:43]
	v_cndmask_b32_e64 v67, v67, v91, s[42:43]
	v_pk_fma_f32 v[34:35], v[50:51], v[34:35], v[54:55]
	v_pk_fma_f32 v[36:37], v[52:53], v[36:37], v[56:57]
	v_pk_fma_f32 v[34:35], v[46:47], v[38:39], v[34:35]
	v_pk_fma_f32 v[36:37], v[48:49], v[66:67], v[36:37]
	v_pk_mul_f32 v[62:63], v[58:59], s[98:99] op_sel_hi:[1,0]
	v_pk_mul_f32 v[64:65], v[60:61], s[98:99] op_sel_hi:[1,0]
	v_exp_f32_e32 v62, v62
	v_exp_f32_e32 v63, v63
	v_exp_f32_e32 v64, v64
	v_exp_f32_e32 v65, v65
	v_pk_add_f32 v[62:63], v[62:63], 1.0 op_sel_hi:[1,0]
	v_pk_add_f32 v[64:65], v[64:65], 1.0 op_sel_hi:[1,0]
	v_rcp_f32_e32 v62, v62
	v_rcp_f32_e32 v63, v63
	v_rcp_f32_e32 v64, v64
	v_rcp_f32_e32 v65, v65
	v_pk_mul_f32 v[58:59], v[58:59], v[62:63]
	v_pk_mul_f32 v[60:61], v[60:61], v[64:65]
	v_pk_fma_f32 v[34:35], v[78:79], v[42:43], v[34:35]
	v_pk_fma_f32 v[36:37], v[76:77], v[44:45], v[36:37]
	v_pk_mul_f32 v[34:35], v[58:59], v[34:35]
	v_pk_mul_f32 v[36:37], v[60:61], v[36:37]
	v_cvt_pk_bf16_f32 v34, v34, v35
	s_nop 0
	v_cvt_pk_bf16_f32 v35, v36, v37
	v_mad_i64_i32 v[36:37], s[0:1], v83, s46, v[40:41]
	v_lshl_add_u64 v[36:37], v[36:37], 0, v[68:69]
	global_store_dwordx2 v[36:37], v[34:35], off
	s_nop 0
	v_and_b32_e32 v108, 15, v226
	v_or_b32_e32 v56, s4, v108
	v_ashrrev_i32_e32 v57, 31, v56
	v_lshl_add_u64 v[40:41], v[56:57], 3, s[38:39]
	global_load_dwordx2 v[42:43], v[40:41], off offset:1024
	global_load_dwordx2 v[38:39], v[40:41], off offset:1152
	global_load_dwordx2 v[36:37], v[40:41], off offset:1280
	s_nop 0
	global_load_dwordx2 v[40:41], v[40:41], off offset:1408
	v_ashrrev_i32_e32 v0, 1, v226
	v_and_b32_e32 v0, -8, v0
	v_add_u32_e32 v34, s21, v0
	s_waitcnt vmcnt(3)
	v_ffbh_u32_e32 v0, v43
	v_min_u32_e32 v0, 32, v0
	v_lshlrev_b64 v[42:43], v0, v[42:43]
	v_min_u32_e32 v35, 1, v42
	v_or_b32_e32 v35, v43, v35
	v_cvt_f32_u32_e32 v35, v35
	v_sub_u32_e32 v0, 32, v0
	v_ldexp_f32 v0, v35, v0
	v_mul_f32_e32 v0, 0x33800000, v0
	v_fmamk_f32 v0, v0, 0x3a800000, v210
	s_nop 0
	v_rsq_f32_e32 v0, v0
	s_nop 0
	s_nop 0
	v_ashrrev_i32_e32 v35, 31, v34
	v_pk_mul_f32 v[84:85], v[32:33], v[0:1] op_sel_hi:[1,0]
	v_pk_mul_f32 v[44:45], v[30:31], v[0:1] op_sel_hi:[1,0]
	v_pk_mul_f32 v[72:73], v[28:29], v[0:1] op_sel_hi:[1,0]
	v_pk_mul_f32 v[42:43], v[26:27], v[0:1] op_sel_hi:[1,0]
	v_lshl_add_u64 v[26:27], v[34:35], 1, s[78:79]
	v_cmp_gt_u32_e32 vcc, 2, v108
	s_and_saveexec_b64 s[0:1], vcc
	s_cbranch_execz .LBB0_129
	v_mul_u32_u24_e32 v0, 0x1600, v108
	v_lshlrev_b32_e32 v0, 1, v0
	v_cvt_pk_bf16_f32 v28, v44, v45
	v_cvt_pk_bf16_f32 v29, v84, v85
	v_lshl_add_u64 v[32:33], v[26:27], 0, v[0:1]
	v_cvt_pk_bf16_f32 v30, v42, v43
	v_cvt_pk_bf16_f32 v31, v72, v73
	global_store_dwordx2 v[32:33], v[28:29], off offset:8
	global_store_dwordx2 v[32:33], v[30:31], off offset:264

.LBB0_131:
	s_or_b64 exec, exec, s[0:1]
	v_ffbh_u32_e32 v0, v39
	v_min_u32_e32 v0, 32, v0
	v_lshlrev_b64 v[14:15], v0, v[38:39]
	v_min_u32_e32 v14, 1, v14
	v_or_b32_e32 v14, v15, v14
	v_cvt_f32_u32_e32 v14, v14
	v_sub_u32_e32 v0, 32, v0
	v_add_u32_e32 v58, s5, v34
	v_ldexp_f32 v0, v14, v0
	v_mul_f32_e32 v0, 0x33800000, v0
	v_fmamk_f32 v0, v0, 0x3a800000, v210
	s_nop 0
	v_rsq_f32_e32 v0, v0
	s_nop 0
	s_nop 0
	v_mov_b32_e32 v52, v0
	v_ffbh_u32_e32 v0, v37
	v_min_u32_e32 v0, 32, v0
	v_lshlrev_b64 v[14:15], v0, v[36:37]
	v_min_u32_e32 v14, 1, v14
	v_or_b32_e32 v14, v15, v14
	v_cvt_f32_u32_e32 v14, v14
	v_sub_u32_e32 v0, 32, v0
	v_pk_mul_f32 v[60:61], v[20:21], v[52:53] op_sel_hi:[1,0]
	v_pk_mul_f32 v[54:55], v[18:19], v[52:53] op_sel_hi:[1,0]
	v_ldexp_f32 v0, v14, v0
	v_mul_f32_e32 v0, 0x33800000, v0
	v_fmamk_f32 v0, v0, 0x3a800000, v210
	s_nop 0
	v_rsq_f32_e32 v0, v0
	s_nop 0
	s_nop 0
	v_mov_b32_e32 v62, v0
	v_pk_mul_f32 v[88:89], v[12:13], v[62:63] op_sel_hi:[1,0]
	v_pk_mul_f32 v[82:83], v[10:11], v[62:63] op_sel_hi:[1,0]
	v_ashrrev_i32_e32 v59, 31, v58
	v_lshlrev_b64 v[22:23], 2, v[58:59]
	v_lshl_add_u64 v[10:11], s[44:45], 0, v[22:23]
	v_lshl_add_u64 v[12:13], s[60:61], 0, v[22:23]
	global_load_dwordx4 v[26:29], v[10:11], off
	global_load_dwordx4 v[30:33], v[12:13], off
	v_lshl_add_u64 v[10:11], s[2:3], 0, v[22:23]
	global_load_dwordx4 v[34:37], v[10:11], off
	v_lshl_add_u64 v[10:11], s[48:49], 0, v[22:23]
	global_load_dwordx4 v[38:41], v[10:11], off
	s_nop 1
	v_cmp_lt_u32_e32 vcc, 1, v108
	v_mov_b32_dpp v66, v44 row_ror:1 row_mask:0xf bank_mask:0xf
	v_mov_b32_dpp v87, v44 row_ror:2 row_mask:0xf bank_mask:0xf
	v_mov_b32_dpp v67, v45 row_ror:1 row_mask:0xf bank_mask:0xf
	v_mov_b32_dpp v86, v45 row_ror:2 row_mask:0xf bank_mask:0xf
	v_mov_b32_dpp v80, v84 row_ror:1 row_mask:0xf bank_mask:0xf
	v_mov_b32_dpp v91, v84 row_ror:2 row_mask:0xf bank_mask:0xf
	v_mov_b32_dpp v81, v85 row_ror:1 row_mask:0xf bank_mask:0xf
	v_mov_b32_dpp v90, v85 row_ror:2 row_mask:0xf bank_mask:0xf
	v_mov_b32_dpp v0, v54 row_ror:1 row_mask:0xf bank_mask:0xf
	v_mov_b32_dpp v97, v54 row_ror:2 row_mask:0xf bank_mask:0xf
	v_mov_b32_dpp v109, v55 row_ror:1 row_mask:0xf bank_mask:0xf
	v_mov_b32_dpp v96, v55 row_ror:2 row_mask:0xf bank_mask:0xf
	v_mov_b32_dpp v110, v60 row_ror:1 row_mask:0xf bank_mask:0xf
	v_mov_b32_dpp v99, v60 row_ror:2 row_mask:0xf bank_mask:0xf
	v_mov_b32_dpp v111, v61 row_ror:1 row_mask:0xf bank_mask:0xf
	v_mov_b32_dpp v98, v61 row_ror:2 row_mask:0xf bank_mask:0xf
	v_mov_b32_dpp v112, v82 row_ror:1 row_mask:0xf bank_mask:0xf
	v_mov_b32_dpp v93, v82 row_ror:2 row_mask:0xf bank_mask:0xf
	v_mov_b32_dpp v113, v83 row_ror:1 row_mask:0xf bank_mask:0xf
	v_mov_b32_dpp v92, v83 row_ror:2 row_mask:0xf bank_mask:0xf
	v_mov_b32_dpp v114, v88 row_ror:1 row_mask:0xf bank_mask:0xf
	v_mov_b32_dpp v95, v88 row_ror:2 row_mask:0xf bank_mask:0xf
	v_mov_b32_dpp v115, v89 row_ror:1 row_mask:0xf bank_mask:0xf
	v_mov_b32_dpp v94, v89 row_ror:2 row_mask:0xf bank_mask:0xf
	v_mov_b32_dpp v57, v64 row_ror:1 row_mask:0xf bank_mask:0xf
	v_mov_b32_dpp v101, v64 row_ror:2 row_mask:0xf bank_mask:0xf
	v_mov_b32_dpp v116, v65 row_ror:1 row_mask:0xf bank_mask:0xf
	v_mov_b32_dpp v100, v65 row_ror:2 row_mask:0xf bank_mask:0xf
	v_mov_b32_dpp v117, v68 row_ror:1 row_mask:0xf bank_mask:0xf
	v_mov_b32_dpp v103, v68 row_ror:2 row_mask:0xf bank_mask:0xf
	v_mov_b32_dpp v118, v69 row_ror:1 row_mask:0xf bank_mask:0xf
	v_mov_b32_dpp v102, v69 row_ror:2 row_mask:0xf bank_mask:0xf
	v_cmp_gt_u32_e64 s[42:43], 2, v108
	v_lshl_add_u64 v[10:11], s[96:97], 0, v[22:23]
	v_lshl_add_u64 v[12:13], s[62:63], 0, v[22:23]
	global_load_dwordx4 v[18:21], v[10:11], off
	global_load_dwordx4 v[14:17], v[12:13], off
	v_lshl_add_u64 v[10:11], s[64:65], 0, v[22:23]
	v_lshl_add_u64 v[22:23], s[66:67], 0, v[22:23]
	global_load_dwordx4 v[10:13], v[10:11], off
	s_nop 1
	global_load_dwordx4 v[22:25], v[22:23], off
	s_nop 1
	v_mov_b32_dpp v70, v42 row_ror:1 row_mask:0xf bank_mask:0xf
	v_mov_b32_dpp v76, v42 row_ror:2 row_mask:0xf bank_mask:0xf
	v_mov_b32_dpp v71, v43 row_ror:1 row_mask:0xf bank_mask:0xf
	v_mov_b32_dpp v77, v43 row_ror:2 row_mask:0xf bank_mask:0xf
	v_mov_b32_dpp v74, v72 row_ror:1 row_mask:0xf bank_mask:0xf
	v_mov_b32_dpp v78, v72 row_ror:2 row_mask:0xf bank_mask:0xf
	v_mov_b32_dpp v75, v73 row_ror:1 row_mask:0xf bank_mask:0xf
	v_mov_b32_dpp v79, v73 row_ror:2 row_mask:0xf bank_mask:0xf
	s_and_saveexec_b64 s[0:1], s[42:43]
	s_xor_b64 s[0:1], exec, s[0:1]
	s_or_saveexec_b64 s[0:1], s[0:1]
	v_mov_b64_e32 v[106:107], v[98:99]
	v_mov_b64_e32 v[104:105], v[96:97]
	s_xor_b64 exec, exec, s[0:1]
	s_cbranch_execz .Lcg_skip3
	s_waitcnt vmcnt(4)
	v_pk_fma_f32 v[46:47], v[28:29], v[90:91], v[40:41] op_sel:[0,1,0] op_sel_hi:[1,0,1]
	v_mov_b64_e32 v[106:107], v[94:95]
	v_pk_fma_f32 v[46:47], v[32:33], v[80:81], v[46:47]
	v_mov_b64_e32 v[104:105], v[92:93]
	v_pk_fma_f32 v[46:47], v[84:85], v[36:37], v[46:47]
	v_pk_fma_f32 v[84:85], v[26:27], v[86:87], v[38:39] op_sel:[0,1,0] op_sel_hi:[1,0,1]
	v_pk_fma_f32 v[84:85], v[30:31], v[66:67], v[84:85]
	v_pk_fma_f32 v[44:45], v[44:45], v[34:35], v[84:85]
	v_pk_mul_f32 v[86:87], v[46:47], s[98:99] op_sel_hi:[1,0]
	v_exp_f32_e32 v86, v86
	v_exp_f32_e32 v87, v87
	s_nop 0
	v_pk_add_f32 v[86:87], v[86:87], 1.0 op_sel_hi:[1,0]
	v_rcp_f32_e32 v86, v86
	v_rcp_f32_e32 v87, v87
	s_nop 0
	v_pk_mul_f32 v[46:47], v[46:47], v[86:87]
	s_waitcnt vmcnt(0)
	v_pk_fma_f32 v[86:87], v[18:19], v[76:77], v[22:23]
	v_add_u32_e32 v53, 0x80, v56
	v_pk_fma_f32 v[86:87], v[14:15], v[70:71], v[86:87]
	v_pk_mul_f32 v[84:85], v[44:45], s[98:99] op_sel_hi:[1,0]
	v_exp_f32_e32 v84, v84
	v_exp_f32_e32 v85, v85
	s_nop 0
	v_pk_add_f32 v[84:85], v[84:85], 1.0 op_sel_hi:[1,0]
	v_rcp_f32_e32 v84, v84
	v_rcp_f32_e32 v85, v85
	s_nop 0
	v_pk_mul_f32 v[44:45], v[44:45], v[84:85]
	v_pk_fma_f32 v[42:43], v[42:43], v[10:11], v[86:87]
	v_pk_fma_f32 v[84:85], v[20:21], v[78:79], v[24:25]
	v_pk_mul_f32 v[42:43], v[44:45], v[42:43]
	v_mov_b64_e32 v[44:45], s[36:37]
	v_pk_fma_f32 v[84:85], v[16:17], v[74:75], v[84:85]
	v_mad_i64_i32 v[44:45], s[4:5], v53, s46, v[44:45]
	v_pk_fma_f32 v[72:73], v[72:73], v[12:13], v[84:85]
	v_lshl_add_u64 v[44:45], v[58:59], 1, v[44:45]
	v_mov_b64_e32 v[90:91], v[98:99]
	v_mov_b64_e32 v[86:87], v[96:97]
	v_mov_b64_e32 v[94:95], v[102:103]
	v_mov_b64_e32 v[92:93], v[100:101]
	v_pk_mul_f32 v[46:47], v[46:47], v[72:73]
	v_cvt_pk_bf16_f32 v42, v42, v43
	s_nop 0
	v_cvt_pk_bf16_f32 v43, v46, v47
	global_store_dwordx2 v[44:45], v[42:43], off
.LBB0_135:
	s_or_b64 exec, exec, s[0:1]
	v_cmp_eq_u32_e64 s[42:43], 0, v108
	v_add_u32_e32 v96, 0x90, v56
	v_add_u32_e32 v97, 0xa0, v56
	v_add_u32_e32 v98, 0xb0, v56
	v_cndmask_b32_e64 v43, v118, v115, s[42:43]
	v_cndmask_b32_e64 v42, v117, v114, s[42:43]
	s_waitcnt vmcnt(4)
	v_pk_fma_f32 v[44:45], v[28:29], v[94:95], v[40:41] op_sel:[0,1,0] op_sel_hi:[1,0,1]
	v_cndmask_b32_e64 v47, v116, v113, s[42:43]
	v_cndmask_b32_e64 v46, v57, v112, s[42:43]
	v_pk_fma_f32 v[56:57], v[26:27], v[92:93], v[38:39] op_sel:[0,1,0] op_sel_hi:[1,0,1]
	v_pk_fma_f32 v[42:43], v[32:33], v[42:43], v[44:45]
	v_pk_fma_f32 v[46:47], v[30:31], v[46:47], v[56:57]
	v_pk_fma_f32 v[42:43], v[68:69], v[36:37], v[42:43]
	v_pk_fma_f32 v[46:47], v[64:65], v[34:35], v[46:47]
	v_cndmask_b32_e64 v65, v115, v111, s[42:43]
	v_cndmask_b32_e64 v64, v114, v110, s[42:43]
	v_pk_fma_f32 v[68:69], v[28:29], v[106:107], v[40:41] op_sel:[0,1,0] op_sel_hi:[1,0,1]
	v_cndmask_b32_e64 v81, v111, v81, s[42:43]
	v_cndmask_b32_e64 v80, v110, v80, s[42:43]
	v_pk_fma_f32 v[28:29], v[28:29], v[90:91], v[40:41] op_sel:[0,1,0] op_sel_hi:[1,0,1]
	v_pk_fma_f32 v[64:65], v[32:33], v[64:65], v[68:69]
	v_pk_fma_f32 v[28:29], v[32:33], v[80:81], v[28:29]
	v_pk_fma_f32 v[64:65], v[88:89], v[36:37], v[64:65]
	v_pk_fma_f32 v[84:85], v[26:27], v[104:105], v[38:39] op_sel:[0,1,0] op_sel_hi:[1,0,1]
	v_pk_fma_f32 v[28:29], v[60:61], v[36:37], v[28:29]
	v_cndmask_b32_e64 v37, v109, v67, s[42:43]
	v_cndmask_b32_e64 v36, v0, v66, s[42:43]
	v_pk_fma_f32 v[26:27], v[26:27], v[86:87], v[38:39] op_sel:[0,1,0] op_sel_hi:[1,0,1]
	v_cndmask_b32_e64 v72, v112, v0, s[42:43]
	v_pk_fma_f32 v[26:27], v[30:31], v[36:37], v[26:27]
	v_pk_fma_f32 v[26:27], v[54:55], v[34:35], v[26:27]
	v_cndmask_b32_e64 v73, v113, v109, s[42:43]
	v_pk_fma_f32 v[72:73], v[30:31], v[72:73], v[84:85]
	v_pk_fma_f32 v[72:73], v[82:83], v[34:35], v[72:73]
	v_mov_b32_e32 v34, v62
	v_mov_b32_e32 v35, v62
	v_mov_b32_e32 v53, v52
	v_mov_b32_e32 v63, v62
	v_pk_mul_f32 v[4:5], v[4:5], v[34:35]
	v_mov_b32_e32 v34, v52
	v_mov_b32_e32 v35, v52
	v_pk_mul_f32 v[2:3], v[2:3], v[62:63]
	v_pk_mul_f32 v[8:9], v[8:9], v[34:35]
	v_pk_mul_f32 v[6:7], v[6:7], v[52:53]
	s_nop 1
	v_mov_b32_dpp v52, v6 row_ror:2 row_mask:0xf bank_mask:0xf
	s_nop 1
	v_mov_b32_dpp v54, v7 row_ror:2 row_mask:0xf bank_mask:0xf
	s_nop 1
	v_mov_b32_dpp v60, v8 row_ror:2 row_mask:0xf bank_mask:0xf
	s_nop 1
	v_mov_b32_dpp v62, v9 row_ror:2 row_mask:0xf bank_mask:0xf
	v_mov_b32_dpp v0, v6 row_ror:1 row_mask:0xf bank_mask:0xf
	v_mov_b32_dpp v53, v7 row_ror:1 row_mask:0xf bank_mask:0xf
	v_mov_b32_dpp v55, v8 row_ror:1 row_mask:0xf bank_mask:0xf
	v_mov_b32_dpp v61, v9 row_ror:1 row_mask:0xf bank_mask:0xf
	v_cndmask_b32_e32 v34, v76, v52, vcc
	v_cndmask_b32_e32 v35, v77, v54, vcc
	v_cndmask_b32_e32 v36, v78, v60, vcc
	v_cndmask_b32_e32 v37, v79, v62, vcc
	v_cndmask_b32_e64 v38, v0, v70, s[42:43]
	v_cndmask_b32_e64 v39, v53, v71, s[42:43]
	v_cndmask_b32_e64 v40, v55, v74, s[42:43]
	v_cndmask_b32_e64 v41, v61, v75, s[42:43]
	v_pk_mul_f32 v[30:31], v[26:27], s[98:99] op_sel_hi:[1,0]
	v_pk_mul_f32 v[32:33], v[28:29], s[98:99] op_sel_hi:[1,0]
	v_exp_f32_e32 v30, v30
	v_exp_f32_e32 v31, v31
	v_exp_f32_e32 v32, v32
	v_exp_f32_e32 v33, v33
	v_pk_add_f32 v[30:31], v[30:31], 1.0 op_sel_hi:[1,0]
	v_pk_add_f32 v[32:33], v[32:33], 1.0 op_sel_hi:[1,0]
	v_rcp_f32_e32 v30, v30
	v_rcp_f32_e32 v31, v31
	v_rcp_f32_e32 v32, v32
	v_rcp_f32_e32 v33, v33
	v_pk_mul_f32 v[26:27], v[26:27], v[30:31]
	v_pk_mul_f32 v[28:29], v[28:29], v[32:33]
	s_waitcnt vmcnt(1)
	v_pk_fma_f32 v[30:31], v[20:21], v[36:37], v[24:25]
	v_pk_fma_f32 v[32:33], v[18:19], v[34:35], v[22:23]
	v_pk_fma_f32 v[30:31], v[16:17], v[40:41], v[30:31]
	v_pk_fma_f32 v[32:33], v[14:15], v[38:39], v[32:33]
	v_pk_fma_f32 v[8:9], v[8:9], v[12:13], v[30:31]
	v_pk_fma_f32 v[6:7], v[6:7], v[10:11], v[32:33]
	v_pk_mul_f32 v[8:9], v[28:29], v[8:9]
	v_pk_mul_f32 v[6:7], v[26:27], v[6:7]
	v_cvt_pk_bf16_f32 v6, v6, v7
	v_cvt_pk_bf16_f32 v7, v8, v9
	v_mov_b64_e32 v[8:9], s[36:37]
	v_mad_i64_i32 v[26:27], s[0:1], v96, s46, v[8:9]
	v_lshlrev_b64 v[28:29], 1, v[58:59]
	s_nop 1
	v_lshl_add_u64 v[26:27], v[26:27], 0, v[28:29]
	s_nop 1
	v_mov_b32_dpp v39, v2 row_ror:2 row_mask:0xf bank_mask:0xf
	s_nop 1
	v_mov_b32_dpp v41, v3 row_ror:2 row_mask:0xf bank_mask:0xf
	s_nop 1
	v_mov_b32_dpp v59, v4 row_ror:2 row_mask:0xf bank_mask:0xf
	s_nop 1
	v_mov_b32_dpp v66, v5 row_ror:2 row_mask:0xf bank_mask:0xf
	global_store_dwordx2 v[26:27], v[6:7], off
	v_mov_b32_dpp v38, v2 row_ror:1 row_mask:0xf bank_mask:0xf
	v_mov_b32_dpp v40, v3 row_ror:1 row_mask:0xf bank_mask:0xf
	v_mov_b32_dpp v58, v4 row_ror:1 row_mask:0xf bank_mask:0xf
	v_mov_b32_dpp v63, v5 row_ror:1 row_mask:0xf bank_mask:0xf
	v_cndmask_b32_e32 v6, v52, v39, vcc
	v_cndmask_b32_e32 v7, v54, v41, vcc
	v_cndmask_b32_e32 v26, v60, v59, vcc
	v_cndmask_b32_e32 v27, v62, v66, vcc
	v_cndmask_b32_e64 v30, v38, v0, s[42:43]
	v_cndmask_b32_e64 v31, v40, v53, s[42:43]
	v_cndmask_b32_e64 v32, v58, v55, s[42:43]
	v_cndmask_b32_e64 v33, v63, v61, s[42:43]
	v_pk_fma_f32 v[26:27], v[20:21], v[26:27], v[24:25]
	v_pk_fma_f32 v[6:7], v[18:19], v[6:7], v[22:23]
	v_pk_fma_f32 v[26:27], v[16:17], v[32:33], v[26:27]
	v_pk_fma_f32 v[6:7], v[14:15], v[30:31], v[6:7]
	v_pk_mul_f32 v[82:83], v[72:73], s[98:99] op_sel_hi:[1,0]
	v_pk_mul_f32 v[68:69], v[64:65], s[98:99] op_sel_hi:[1,0]
	v_exp_f32_e32 v82, v82
	v_exp_f32_e32 v83, v83
	v_exp_f32_e32 v68, v68
	v_exp_f32_e32 v69, v69
	v_pk_add_f32 v[82:83], v[82:83], 1.0 op_sel_hi:[1,0]
	v_pk_add_f32 v[68:69], v[68:69], 1.0 op_sel_hi:[1,0]
	v_rcp_f32_e32 v82, v82
	v_rcp_f32_e32 v83, v83
	v_rcp_f32_e32 v68, v68
	v_rcp_f32_e32 v69, v69
	v_pk_mul_f32 v[34:35], v[72:73], v[82:83]
	v_pk_mul_f32 v[36:37], v[64:65], v[68:69]
	v_pk_fma_f32 v[4:5], v[4:5], v[12:13], v[26:27]
	v_pk_fma_f32 v[2:3], v[2:3], v[10:11], v[6:7]
	v_pk_mul_f32 v[4:5], v[36:37], v[4:5]
	v_pk_mul_f32 v[2:3], v[34:35], v[2:3]
	v_cvt_pk_bf16_f32 v2, v2, v3
	v_cvt_pk_bf16_f32 v3, v4, v5
	v_mad_i64_i32 v[4:5], s[0:1], v97, s46, v[8:9]
	v_lshl_add_u64 v[4:5], v[4:5], 0, v[28:29]
	global_store_dwordx2 v[4:5], v[2:3], off
	s_nop 1
	s_nop 1
	v_mov_b32_dpp v2, v50 row_ror:2 row_mask:0xf bank_mask:0xf
	s_nop 1
	v_mov_b32_dpp v3, v51 row_ror:2 row_mask:0xf bank_mask:0xf
	s_nop 1
	v_mov_b32_dpp v4, v48 row_ror:2 row_mask:0xf bank_mask:0xf
	s_nop 1
	v_mov_b32_dpp v5, v49 row_ror:2 row_mask:0xf bank_mask:0xf
	v_mov_b32_dpp v0, v50 row_ror:1 row_mask:0xf bank_mask:0xf
	v_mov_b32_dpp v7, v51 row_ror:1 row_mask:0xf bank_mask:0xf
	v_mov_b32_dpp v26, v48 row_ror:1 row_mask:0xf bank_mask:0xf
	v_mov_b32_dpp v27, v49 row_ror:1 row_mask:0xf bank_mask:0xf
	v_cndmask_b32_e32 v2, v39, v2, vcc
	v_cndmask_b32_e32 v3, v41, v3, vcc
	v_cndmask_b32_e32 v4, v59, v4, vcc
	v_cndmask_b32_e32 v5, v66, v5, vcc
	v_cndmask_b32_e64 v6, v0, v38, s[42:43]
	v_cndmask_b32_e64 v7, v7, v40, s[42:43]
	v_cndmask_b32_e64 v26, v26, v58, s[42:43]
	v_cndmask_b32_e64 v27, v27, v63, s[42:43]
	v_pk_fma_f32 v[2:3], v[18:19], v[2:3], v[22:23]
	v_pk_fma_f32 v[4:5], v[20:21], v[4:5], v[24:25]
	v_pk_fma_f32 v[2:3], v[14:15], v[6:7], v[2:3]
	v_pk_fma_f32 v[4:5], v[16:17], v[26:27], v[4:5]
	v_pk_mul_f32 v[56:57], v[46:47], s[98:99] op_sel_hi:[1,0]
	v_pk_mul_f32 v[44:45], v[42:43], s[98:99] op_sel_hi:[1,0]
	v_exp_f32_e32 v56, v56
	v_exp_f32_e32 v57, v57
	v_exp_f32_e32 v44, v44
	v_exp_f32_e32 v45, v45
	v_pk_add_f32 v[56:57], v[56:57], 1.0 op_sel_hi:[1,0]
	v_pk_add_f32 v[44:45], v[44:45], 1.0 op_sel_hi:[1,0]
	v_rcp_f32_e32 v56, v56
	v_rcp_f32_e32 v57, v57
	v_rcp_f32_e32 v44, v44
	v_rcp_f32_e32 v45, v45
	v_pk_mul_f32 v[30:31], v[46:47], v[56:57]
	v_pk_mul_f32 v[32:33], v[42:43], v[44:45]
	v_pk_fma_f32 v[2:3], v[50:51], v[10:11], v[2:3]
	v_pk_fma_f32 v[4:5], v[48:49], v[12:13], v[4:5]
	v_pk_mul_f32 v[2:3], v[30:31], v[2:3]
	v_pk_mul_f32 v[4:5], v[32:33], v[4:5]
	v_cvt_pk_bf16_f32 v2, v2, v3
	s_nop 0
	v_cvt_pk_bf16_f32 v3, v4, v5
	v_mad_i64_i32 v[4:5], s[0:1], v98, s46, v[8:9]
	v_lshl_add_u64 v[4:5], v[4:5], 0, v[28:29]
	global_store_dwordx2 v[4:5], v[2:3], off
	s_andn2_b64 vcc, exec, s[40:41]
	s_mov_b64 s[0:1], -1
	s_cbranch_vccnz .LBB0_102
	s_andn2_b64 vcc, exec, s[30:31]
	s_cbranch_vccnz .LBB0_101
	s_barrier
	s_branch .LBB0_101
